# LDS read addresses in the P6/P7 K-loops: one biased base VGPR + immediate offsets (the 4 v_add_u32 per iteration removed)
# speedup vs baseline: 1.0175x; 1.0022x over previous
.LBB0_1221:
	s_add_u32 s14, s96, 0xa0000
	s_addc_u32 s15, s97, 0
	s_add_u32 s16, s96, 0x80000
	s_addc_u32 s17, s97, 0
	s_lshl_b32 s20, s20, 5
	s_and_b32 s50, s20, 0x60
	s_mov_b64 s[20:21], 0x80
	s_add_i32 m0, s45, 0x18000
	v_lshl_add_u64 v[6:7], v[6:7], 0, s[20:21]
	s_lshl_b32 s49, s8, 6
	s_lshl_b32 s8, s8, 13
	s_lshl_b32 s23, s50, 7
	s_waitcnt vmcnt(2)
	s_barrier
	global_load_lds_dwordx4 v[6:7], off
	v_lshl_add_u64 v[4:5], v[4:5], 0, s[20:21]
	s_add_i32 m0, s45, 0x1a000
	s_add_i32 s51, s45, 0x8000
	s_add_i32 s52, s45, 0xa000
	global_load_lds_dwordx4 v[4:5], off
	v_lshl_add_u64 v[0:1], v[0:1], 0, s[20:21]
	s_mov_b32 m0, s51
	s_add_u32 s24, s38, 0x80080
	global_load_lds_dwordx4 v[0:1], off
	v_lshl_add_u64 v[0:1], v[2:3], 0, s[20:21]
	s_mov_b32 m0, s52
	s_addc_u32 s25, s39, 0
	global_load_lds_dwordx4 v[0:1], off
	s_add_i32 m0, s45, 0x1c000
	v_lshl_add_u64 v[0:1], s[24:25], 0, v[130:131]
	global_load_lds_dwordx4 v[0:1], off
	v_lshl_add_u64 v[0:1], s[24:25], 0, v[134:135]
	s_add_i32 m0, s45, 0x1e000
	v_bfe_u32 v176, v8, 4, 2
	global_load_lds_dwordx4 v[0:1], off
	v_and_b32_e32 v175, 15, v8
	v_lshlrev_b32_e32 v0, 4, v176
	v_lshlrev_b32_e32 v1, 2, v8
	v_lshl_or_b32 v0, v175, 6, v0
	v_and_b32_e32 v1, 32, v1
	v_bitop3_b32 v2, v0, s8, v1 bitop3:0xde
	v_bitop3_b32 v177, v0, s23, v1 bitop3:0xde
	v_add_u32_e32 v177, 0x10000, v177
	v_lshlrev_b32_e32 v0, 15, v9
	v_and_b32_e32 v0, 0xffff0000, v0
	v_lshl_add_u32 v0, v10, 12, v0
	v_and_b32_e32 v1, 1, v9
	v_lshl_or_b32 v0, v1, 6, v0
	v_lshl_add_u32 v136, v11, 1, v0
	v_lshlrev_b32_e32 v0, 15, v12
	v_and_b32_e32 v0, 0xffff0000, v0
	s_waitcnt vmcnt(6)
	s_cmpk_lt_u32 s22, 0x100
	v_lshl_add_u32 v0, v13, 12, v0
	v_and_b32_e32 v1, 1, v12
	s_cselect_b64 s[22:23], -1, 0
	s_cmp_lt_i32 s3, 64
	v_lshl_or_b32 v0, v1, 6, v0
	s_cselect_b64 s[24:25], -1, 0
	s_lshl_b32 s53, s3, 2
	s_add_i32 s54, s3, 0xc0
	v_mov_b32_e32 v137, v131
	v_lshl_add_u32 v138, v14, 1, v0
	v_mov_b32_e32 v139, v131
	s_add_i32 s55, 0, 0x10000
	s_add_i32 s60, 0, 0x14000
	v_add_u32_e32 v178, 0, v2
	s_mov_b32 s26, 0x3c010204
	s_mov_b32 s61, 0x15800
	s_movk_i32 s62, 0x5600
	s_mov_b32 s63, 0
	s_barrier
	s_cmp_lt_u32 s84, s87
	s_cbranch_scc0 .Lq_init_done
	s_mov_b32 s75, 0x42fe0000
	v_div_scale_f32 v236, vcc, v240, v240, s75
	v_rcp_f32_e32 v237, v236
	s_nop 1
	v_fma_f32 v238, -v236, v237, 1.0
	v_fmac_f32_e32 v237, v238, v237
	v_div_scale_f32 v238, vcc, s75, v240, s75
	v_mul_f32_e32 v239, v238, v237
	v_fma_f32 v244, -v236, v239, v238
	v_fmac_f32_e32 v239, v244, v237
	v_fma_f32 v236, -v236, v239, v238
	s_nop 4
	v_div_fmas_f32 v236, v236, v237, v239
	v_div_fixup_f32 v236, v236, v240, s75
	v_cmp_lt_f32_e32 vcc, 0, v240
	s_nop 1
	v_cndmask_b32_e32 v220, 0, v236, vcc
	v_div_scale_f32 v236, vcc, v241, v241, s75
	v_rcp_f32_e32 v237, v236
	s_nop 1
	v_fma_f32 v238, -v236, v237, 1.0
	v_fmac_f32_e32 v237, v238, v237
	v_div_scale_f32 v238, vcc, s75, v241, s75
	v_mul_f32_e32 v239, v238, v237
	v_fma_f32 v244, -v236, v239, v238
	v_fmac_f32_e32 v239, v244, v237
	v_fma_f32 v236, -v236, v239, v238
	s_nop 4
	v_div_fmas_f32 v236, v236, v237, v239
	v_div_fixup_f32 v236, v236, v241, s75
	v_cmp_lt_f32_e32 vcc, 0, v241
	s_nop 1
	v_cndmask_b32_e32 v225, 0, v236, vcc
	v_div_scale_f32 v236, vcc, v242, v242, s75
	v_rcp_f32_e32 v237, v236
	s_nop 1
	v_fma_f32 v238, -v236, v237, 1.0
	v_fmac_f32_e32 v237, v238, v237
	v_div_scale_f32 v238, vcc, s75, v242, s75
	v_mul_f32_e32 v239, v238, v237
	v_fma_f32 v244, -v236, v239, v238
	v_fmac_f32_e32 v239, v244, v237
	v_fma_f32 v236, -v236, v239, v238
	s_nop 4
	v_div_fmas_f32 v236, v236, v237, v239
	v_div_fixup_f32 v236, v236, v242, s75
	v_cmp_lt_f32_e32 vcc, 0, v242
	s_nop 1
	v_cndmask_b32_e32 v252, 0, v236, vcc
	v_div_scale_f32 v236, vcc, v243, v243, s75
	v_rcp_f32_e32 v237, v236
	s_nop 1
	v_fma_f32 v238, -v236, v237, 1.0
	v_fmac_f32_e32 v237, v238, v237
	v_div_scale_f32 v238, vcc, s75, v243, s75
	v_mul_f32_e32 v239, v238, v237
	v_fma_f32 v244, -v236, v239, v238
	v_fmac_f32_e32 v239, v244, v237
	v_fma_f32 v236, -v236, v239, v238
	s_nop 4
	v_div_fmas_f32 v236, v236, v237, v239
	v_div_fixup_f32 v236, v236, v243, s75
	v_cmp_lt_f32_e32 vcc, 0, v243
	s_nop 1
	v_cndmask_b32_e32 v253, 0, v236, vcc
	s_lshr_b32 s76, s84, 4
	s_lshr_b32 s77, s76, 1
	s_mul_i32 s77, s77, 0x17d07
	s_lshr_b32 s77, s77, 22
	s_add_u32 s89, s77, 1
	s_mul_i32 s89, s89, 0x560
	s_mul_i32 s75, s77, 86
	s_sub_u32 s76, s76, s75
	s_lshl_b32 s76, s76, 7
	s_mul_i32 s98, s77, 0x56000
	s_add_u32 s98, s98, s76
	s_add_u32 s98, s96, s98
	s_addc_u32 s99, s97, 0
	s_and_b32 s75, s84, 15
	s_add_u32 s76, s76, s75
	s_lshl_b32 s76, s76, 14
	s_lshl_b32 s77, s77, 7
	s_add_u32 s76, s76, s77
	s_load_dwordx2 s[100:101], s[0:1], 0x88
	s_waitcnt lgkmcnt(0)
	s_add_u32 s100, s100, s76
	s_addc_u32 s101, s101, 0
	s_mov_b32 s32, 1

.LBB0_1238:
	s_add_i32 s74, s38, 2
	s_add_u32 s39, s36, 0xfff80080
	s_addc_u32 s40, s37, -1
	s_cmp_eq_u32 s71, s38
	s_cselect_b32 s41, s67, s40
	s_cselect_b32 s40, s68, s39
	ds_read_b128 v[140:143], v177
	ds_read_b128 v[144:147], v177 offset:1024
	ds_read_b128 v[148:151], v177 offset:2048
	ds_read_b128 v[152:155], v177 offset:3072
	ds_read_b128 v[156:159], v177 offset:16384
	ds_read_b128 v[160:163], v177 offset:17408
	ds_read_b128 v[164:167], v177 offset:18432
	ds_read_b128 v[168:171], v177 offset:19456
	s_cselect_b32 s38, s70, s72
	s_cselect_b32 s39, s69, s73
	s_add_i32 m0, s45, 0xc000
	ds_read_b128 v[180:183], v178
	ds_read_b128 v[184:187], v178 offset:1024
	ds_read_b128 v[188:191], v178 offset:2048
	ds_read_b128 v[192:195], v178 offset:3072
	ds_read_b128 v[196:199], v178 offset:4096
	ds_read_b128 v[200:203], v178 offset:5120
	ds_read_b128 v[204:207], v178 offset:6144
	ds_read_b128 v[208:211], v178 offset:7168
	global_load_lds_dwordx4 v136, s[36:37]
	s_add_i32 m0, s45, 0xe000
	s_nop 0
	global_load_lds_dwordx4 v138, s[36:37]
	s_waitcnt vmcnt(8)
	s_waitcnt lgkmcnt(0)
	s_barrier
	s_setprio 1
	s_waitcnt lgkmcnt(0)
	v_mfma_i32_16x16x64_i8 v[124:127], v[140:143], v[180:183], v[124:127]
	v_mfma_i32_16x16x64_i8 v[120:123], v[148:151], v[180:183], v[120:123]
	v_mfma_i32_16x16x64_i8 v[116:119], v[140:143], v[188:191], v[116:119]
	v_mfma_i32_16x16x64_i8 v[112:115], v[148:151], v[188:191], v[112:115]
	v_mfma_i32_16x16x64_i8 v[104:107], v[140:143], v[196:199], v[104:107]
	v_mfma_i32_16x16x64_i8 v[96:99], v[148:151], v[196:199], v[96:99]
	v_mfma_i32_16x16x64_i8 v[88:91], v[140:143], v[204:207], v[88:91]
	v_mfma_i32_16x16x64_i8 v[80:83], v[148:151], v[204:207], v[80:83]
	v_mfma_i32_16x16x64_i8 v[124:127], v[144:147], v[184:187], v[124:127]
	v_mfma_i32_16x16x64_i8 v[120:123], v[152:155], v[184:187], v[120:123]
	v_mfma_i32_16x16x64_i8 v[116:119], v[144:147], v[192:195], v[116:119]
	v_mfma_i32_16x16x64_i8 v[112:115], v[152:155], v[192:195], v[112:115]
	v_mfma_i32_16x16x64_i8 v[104:107], v[144:147], v[200:203], v[104:107]
	v_mfma_i32_16x16x64_i8 v[96:99], v[152:155], v[200:203], v[96:99]
	v_mfma_i32_16x16x64_i8 v[88:91], v[144:147], v[208:211], v[88:91]
	v_mfma_i32_16x16x64_i8 v[80:83], v[152:155], v[208:211], v[80:83]
	s_setprio 0
	s_setprio 1
	v_mfma_i32_16x16x64_i8 v[108:111], v[156:159], v[180:183], v[108:111]
	v_mfma_i32_16x16x64_i8 v[100:103], v[164:167], v[180:183], v[100:103]
	v_mfma_i32_16x16x64_i8 v[92:95], v[156:159], v[188:191], v[92:95]
	v_mfma_i32_16x16x64_i8 v[84:87], v[164:167], v[188:191], v[84:87]
	v_mfma_i32_16x16x64_i8 v[76:79], v[156:159], v[196:199], v[76:79]
	v_mfma_i32_16x16x64_i8 v[72:75], v[164:167], v[196:199], v[72:75]
	v_mfma_i32_16x16x64_i8 v[68:71], v[156:159], v[204:207], v[68:71]
	v_mfma_i32_16x16x64_i8 v[64:67], v[164:167], v[204:207], v[64:67]
	v_mfma_i32_16x16x64_i8 v[108:111], v[160:163], v[184:187], v[108:111]
	v_mfma_i32_16x16x64_i8 v[100:103], v[168:171], v[184:187], v[100:103]
	v_mfma_i32_16x16x64_i8 v[92:95], v[160:163], v[192:195], v[92:95]
	v_mfma_i32_16x16x64_i8 v[84:87], v[168:171], v[192:195], v[84:87]
	v_mfma_i32_16x16x64_i8 v[76:79], v[160:163], v[200:203], v[76:79]
	v_mfma_i32_16x16x64_i8 v[72:75], v[168:171], v[200:203], v[72:75]
	v_mfma_i32_16x16x64_i8 v[68:71], v[160:163], v[208:211], v[68:71]
	v_mfma_i32_16x16x64_i8 v[64:67], v[168:171], v[208:211], v[64:67]
	s_setprio 0
	s_barrier
	s_add_i32 s75, s55, s42
	s_mov_b32 m0, s75
	ds_read_b128 v[180:183], v178 offset:16384
	ds_read_b128 v[184:187], v178 offset:17408
	ds_read_b128 v[188:191], v178 offset:18432
	ds_read_b128 v[192:195], v178 offset:19456
	ds_read_b128 v[196:199], v178 offset:20480
	ds_read_b128 v[200:203], v178 offset:21504
	ds_read_b128 v[204:207], v178 offset:22528
	ds_read_b128 v[208:211], v178 offset:23552
	global_load_lds_dwordx4 v130, s[38:39]
	s_add_i32 m0, s75, 0x2000
	s_add_u32 s76, s38, 0x80000
	s_addc_u32 s77, s39, 0
	s_add_i32 s75, s60, s42
	global_load_lds_dwordx4 v134, s[38:39]
	s_mov_b32 m0, s75
	s_nop 0
	global_load_lds_dwordx4 v130, s[76:77]
	s_add_i32 m0, s75, 0x2000
	s_nop 0
	global_load_lds_dwordx4 v134, s[76:77]
	s_mov_b32 m0, s45
	s_nop 0
	global_load_lds_dwordx4 v128, s[40:41]
	s_mov_b32 m0, s46
	s_nop 0
	global_load_lds_dwordx4 v132, s[40:41]
	s_waitcnt vmcnt(8)
	s_waitcnt lgkmcnt(0)
	s_barrier
	s_setprio 1
	s_waitcnt lgkmcnt(0)
	v_mfma_i32_16x16x64_i8 v[60:63], v[140:143], v[180:183], v[60:63]
	v_mfma_i32_16x16x64_i8 v[56:59], v[148:151], v[180:183], v[56:59]
	v_mfma_i32_16x16x64_i8 v[52:55], v[140:143], v[188:191], v[52:55]
	v_mfma_i32_16x16x64_i8 v[48:51], v[148:151], v[188:191], v[48:51]
	v_mfma_i32_16x16x64_i8 v[40:43], v[140:143], v[196:199], v[40:43]
	v_mfma_i32_16x16x64_i8 v[32:35], v[148:151], v[196:199], v[32:35]
	v_mfma_i32_16x16x64_i8 v[24:27], v[140:143], v[204:207], v[24:27]
	v_mfma_i32_16x16x64_i8 v[16:19], v[148:151], v[204:207], v[16:19]
	v_mfma_i32_16x16x64_i8 v[60:63], v[144:147], v[184:187], v[60:63]
	v_mfma_i32_16x16x64_i8 v[56:59], v[152:155], v[184:187], v[56:59]
	v_mfma_i32_16x16x64_i8 v[52:55], v[144:147], v[192:195], v[52:55]
	v_mfma_i32_16x16x64_i8 v[48:51], v[152:155], v[192:195], v[48:51]
	v_mfma_i32_16x16x64_i8 v[40:43], v[144:147], v[200:203], v[40:43]
	v_mfma_i32_16x16x64_i8 v[32:35], v[152:155], v[200:203], v[32:35]
	v_mfma_i32_16x16x64_i8 v[24:27], v[144:147], v[208:211], v[24:27]
	v_mfma_i32_16x16x64_i8 v[16:19], v[152:155], v[208:211], v[16:19]
	s_setprio 0
	s_setprio 1
	v_mfma_i32_16x16x64_i8 v[44:47], v[156:159], v[180:183], v[44:47]
	v_mfma_i32_16x16x64_i8 v[36:39], v[164:167], v[180:183], v[36:39]
	v_mfma_i32_16x16x64_i8 v[28:31], v[156:159], v[188:191], v[28:31]
	v_mfma_i32_16x16x64_i8 v[20:23], v[164:167], v[188:191], v[20:23]
	v_mfma_i32_16x16x64_i8 v[12:15], v[156:159], v[196:199], v[12:15]
	v_mfma_i32_16x16x64_i8 v[8:11], v[164:167], v[196:199], v[8:11]
	v_mfma_i32_16x16x64_i8 v[4:7], v[156:159], v[204:207], v[4:7]
	v_mfma_i32_16x16x64_i8 v[0:3], v[164:167], v[204:207], v[0:3]
	v_mfma_i32_16x16x64_i8 v[44:47], v[160:163], v[184:187], v[44:47]
	v_mfma_i32_16x16x64_i8 v[36:39], v[168:171], v[184:187], v[36:39]
	v_mfma_i32_16x16x64_i8 v[28:31], v[160:163], v[192:195], v[28:31]
	v_mfma_i32_16x16x64_i8 v[20:23], v[168:171], v[192:195], v[20:23]
	v_mfma_i32_16x16x64_i8 v[12:15], v[160:163], v[200:203], v[12:15]
	v_mfma_i32_16x16x64_i8 v[8:11], v[168:171], v[200:203], v[8:11]
	v_mfma_i32_16x16x64_i8 v[4:7], v[160:163], v[208:211], v[4:7]
	v_mfma_i32_16x16x64_i8 v[0:3], v[168:171], v[208:211], v[0:3]
	s_setprio 0
	s_barrier
	s_add_i32 s75, 0, 0x18000
	s_add_i32 s76, 0, 0x1c000
	ds_read_b128 v[140:143], v177 offset:32768
	ds_read_b128 v[144:147], v177 offset:33792
	ds_read_b128 v[148:151], v177 offset:34816
	ds_read_b128 v[152:155], v177 offset:35840
	ds_read_b128 v[156:159], v177 offset:49152
	ds_read_b128 v[160:163], v177 offset:50176
	ds_read_b128 v[164:167], v177 offset:51200
	ds_read_b128 v[168:171], v177 offset:52224
	s_add_u32 s40, s40, 0x80000
	s_addc_u32 s41, s41, 0
	s_mov_b32 m0, s47
	ds_read_b128 v[180:183], v178 offset:32768
	ds_read_b128 v[184:187], v178 offset:33792
	ds_read_b128 v[188:191], v178 offset:34816
	ds_read_b128 v[192:195], v178 offset:35840
	ds_read_b128 v[196:199], v178 offset:36864
	ds_read_b128 v[200:203], v178 offset:37888
	ds_read_b128 v[204:207], v178 offset:38912
	ds_read_b128 v[208:211], v178 offset:39936
	global_load_lds_dwordx4 v128, s[40:41]
	s_mov_b32 m0, s48
	s_nop 0
	global_load_lds_dwordx4 v132, s[40:41]
	s_waitcnt vmcnt(8)
	s_waitcnt lgkmcnt(0)
	s_barrier
	s_setprio 1
	s_waitcnt lgkmcnt(0)
	v_mfma_i32_16x16x64_i8 v[124:127], v[140:143], v[180:183], v[124:127]
	v_mfma_i32_16x16x64_i8 v[120:123], v[148:151], v[180:183], v[120:123]
	v_mfma_i32_16x16x64_i8 v[116:119], v[140:143], v[188:191], v[116:119]
	v_mfma_i32_16x16x64_i8 v[112:115], v[148:151], v[188:191], v[112:115]
	v_mfma_i32_16x16x64_i8 v[104:107], v[140:143], v[196:199], v[104:107]
	v_mfma_i32_16x16x64_i8 v[96:99], v[148:151], v[196:199], v[96:99]
	v_mfma_i32_16x16x64_i8 v[88:91], v[140:143], v[204:207], v[88:91]
	v_mfma_i32_16x16x64_i8 v[80:83], v[148:151], v[204:207], v[80:83]
	v_mfma_i32_16x16x64_i8 v[124:127], v[144:147], v[184:187], v[124:127]
	v_mfma_i32_16x16x64_i8 v[120:123], v[152:155], v[184:187], v[120:123]
	v_mfma_i32_16x16x64_i8 v[116:119], v[144:147], v[192:195], v[116:119]
	v_mfma_i32_16x16x64_i8 v[112:115], v[152:155], v[192:195], v[112:115]
	v_mfma_i32_16x16x64_i8 v[104:107], v[144:147], v[200:203], v[104:107]
	v_mfma_i32_16x16x64_i8 v[96:99], v[152:155], v[200:203], v[96:99]
	v_mfma_i32_16x16x64_i8 v[88:91], v[144:147], v[208:211], v[88:91]
	v_mfma_i32_16x16x64_i8 v[80:83], v[152:155], v[208:211], v[80:83]
	s_setprio 0
	s_setprio 1
	v_mfma_i32_16x16x64_i8 v[108:111], v[156:159], v[180:183], v[108:111]
	v_mfma_i32_16x16x64_i8 v[100:103], v[164:167], v[180:183], v[100:103]
	v_mfma_i32_16x16x64_i8 v[92:95], v[156:159], v[188:191], v[92:95]
	v_mfma_i32_16x16x64_i8 v[84:87], v[164:167], v[188:191], v[84:87]
	v_mfma_i32_16x16x64_i8 v[76:79], v[156:159], v[196:199], v[76:79]
	v_mfma_i32_16x16x64_i8 v[72:75], v[164:167], v[196:199], v[72:75]
	v_mfma_i32_16x16x64_i8 v[68:71], v[156:159], v[204:207], v[68:71]
	v_mfma_i32_16x16x64_i8 v[64:67], v[164:167], v[204:207], v[64:67]
	v_mfma_i32_16x16x64_i8 v[108:111], v[160:163], v[184:187], v[108:111]
	v_mfma_i32_16x16x64_i8 v[100:103], v[168:171], v[184:187], v[100:103]
	v_mfma_i32_16x16x64_i8 v[92:95], v[160:163], v[192:195], v[92:95]
	v_mfma_i32_16x16x64_i8 v[84:87], v[168:171], v[192:195], v[84:87]
	v_mfma_i32_16x16x64_i8 v[76:79], v[160:163], v[200:203], v[76:79]
	v_mfma_i32_16x16x64_i8 v[72:75], v[168:171], v[200:203], v[72:75]
	v_mfma_i32_16x16x64_i8 v[68:71], v[160:163], v[208:211], v[68:71]
	v_mfma_i32_16x16x64_i8 v[64:67], v[168:171], v[208:211], v[64:67]
	s_setprio 0
	s_barrier
	s_add_u32 s98, s38, s20
	s_addc_u32 s99, s39, s21
	s_add_u32 s100, s40, s20
	s_addc_u32 s101, s41, s21
	s_sub_u32 s100, s100, 0x80000
	s_subb_u32 s101, s101, 0
	s_add_i32 s40, s75, s42
	s_mov_b32 m0, s40
	ds_read_b128 v[180:183], v178 offset:49152
	ds_read_b128 v[184:187], v178 offset:50176
	ds_read_b128 v[188:191], v178 offset:51200
	ds_read_b128 v[192:195], v178 offset:52224
	ds_read_b128 v[196:199], v178 offset:53248
	ds_read_b128 v[200:203], v178 offset:54272
	ds_read_b128 v[204:207], v178 offset:55296
	ds_read_b128 v[208:211], v178 offset:56320
	global_load_lds_dwordx4 v130, s[98:99]
	s_add_i32 m0, s40, 0x2000
	s_add_u32 s38, s38, 0x80080
	s_addc_u32 s39, s39, 0
	s_add_i32 s40, s76, s42
	global_load_lds_dwordx4 v134, s[98:99]
	s_mov_b32 m0, s40
	s_nop 0
	global_load_lds_dwordx4 v130, s[38:39]
	s_add_i32 m0, s40, 0x2000
	s_nop 0
	global_load_lds_dwordx4 v134, s[38:39]
	s_mov_b32 m0, s51
	s_nop 0
	global_load_lds_dwordx4 v128, s[100:101]
	s_mov_b32 m0, s52
	s_nop 0
	global_load_lds_dwordx4 v132, s[100:101]
	s_waitcnt vmcnt(8)
	s_waitcnt lgkmcnt(0)
	s_barrier
	s_setprio 1
	s_waitcnt lgkmcnt(0)
	v_mfma_i32_16x16x64_i8 v[60:63], v[140:143], v[180:183], v[60:63]
	v_mfma_i32_16x16x64_i8 v[56:59], v[148:151], v[180:183], v[56:59]
	v_mfma_i32_16x16x64_i8 v[52:55], v[140:143], v[188:191], v[52:55]
	v_mfma_i32_16x16x64_i8 v[48:51], v[148:151], v[188:191], v[48:51]
	v_mfma_i32_16x16x64_i8 v[40:43], v[140:143], v[196:199], v[40:43]
	v_mfma_i32_16x16x64_i8 v[32:35], v[148:151], v[196:199], v[32:35]
	v_mfma_i32_16x16x64_i8 v[24:27], v[140:143], v[204:207], v[24:27]
	v_mfma_i32_16x16x64_i8 v[16:19], v[148:151], v[204:207], v[16:19]
	v_mfma_i32_16x16x64_i8 v[60:63], v[144:147], v[184:187], v[60:63]
	v_mfma_i32_16x16x64_i8 v[56:59], v[152:155], v[184:187], v[56:59]
	v_mfma_i32_16x16x64_i8 v[52:55], v[144:147], v[192:195], v[52:55]
	v_mfma_i32_16x16x64_i8 v[48:51], v[152:155], v[192:195], v[48:51]
	v_mfma_i32_16x16x64_i8 v[40:43], v[144:147], v[200:203], v[40:43]
	v_mfma_i32_16x16x64_i8 v[32:35], v[152:155], v[200:203], v[32:35]
	v_mfma_i32_16x16x64_i8 v[24:27], v[144:147], v[208:211], v[24:27]
	v_mfma_i32_16x16x64_i8 v[16:19], v[152:155], v[208:211], v[16:19]
	s_setprio 0
	s_setprio 1
	v_mfma_i32_16x16x64_i8 v[44:47], v[156:159], v[180:183], v[44:47]
	v_mfma_i32_16x16x64_i8 v[36:39], v[164:167], v[180:183], v[36:39]
	v_mfma_i32_16x16x64_i8 v[28:31], v[156:159], v[188:191], v[28:31]
	v_mfma_i32_16x16x64_i8 v[20:23], v[164:167], v[188:191], v[20:23]
	v_mfma_i32_16x16x64_i8 v[12:15], v[156:159], v[196:199], v[12:15]
	v_mfma_i32_16x16x64_i8 v[8:11], v[164:167], v[196:199], v[8:11]
	v_mfma_i32_16x16x64_i8 v[4:7], v[156:159], v[204:207], v[4:7]
	v_mfma_i32_16x16x64_i8 v[0:3], v[164:167], v[204:207], v[0:3]
	v_mfma_i32_16x16x64_i8 v[44:47], v[160:163], v[184:187], v[44:47]
	v_mfma_i32_16x16x64_i8 v[36:39], v[168:171], v[184:187], v[36:39]
	v_mfma_i32_16x16x64_i8 v[28:31], v[160:163], v[192:195], v[28:31]
	v_mfma_i32_16x16x64_i8 v[20:23], v[168:171], v[192:195], v[20:23]
	v_mfma_i32_16x16x64_i8 v[12:15], v[160:163], v[200:203], v[12:15]
	v_mfma_i32_16x16x64_i8 v[8:11], v[168:171], v[200:203], v[8:11]
	v_mfma_i32_16x16x64_i8 v[4:7], v[160:163], v[208:211], v[4:7]
	v_mfma_i32_16x16x64_i8 v[0:3], v[168:171], v[208:211], v[0:3]
	s_setprio 0
	s_barrier
	s_add_u32 s36, s36, 0x100
	s_addc_u32 s37, s37, 0
	s_add_u32 s72, s72, 0x100
	s_addc_u32 s73, s73, 0
	s_cmp_ge_i32 s74, s8
	s_mov_b32 s38, s74
	s_cbranch_scc0 .LBB0_1238

.Lq_body_L:
	s_add_i32 s74, s38, 2
	s_add_u32 s39, s36, 0xfff80080
	s_addc_u32 s40, s37, -1
	s_cmp_eq_u32 s71, s38
	s_cselect_b32 s41, s67, s40
	s_cselect_b32 s40, s68, s39
	ds_read_b128 v[140:143], v177
	ds_read_b128 v[144:147], v177 offset:1024
	ds_read_b128 v[148:151], v177 offset:2048
	ds_read_b128 v[152:155], v177 offset:3072
	ds_read_b128 v[156:159], v177 offset:16384
	ds_read_b128 v[160:163], v177 offset:17408
	ds_read_b128 v[164:167], v177 offset:18432
	ds_read_b128 v[168:171], v177 offset:19456
	s_cselect_b32 s38, s70, s72
	s_cselect_b32 s39, s69, s73
	s_add_i32 m0, s45, 0xc000
	ds_read_b128 v[180:183], v178
	ds_read_b128 v[184:187], v178 offset:1024
	ds_read_b128 v[188:191], v178 offset:2048
	ds_read_b128 v[192:195], v178 offset:3072
	ds_read_b128 v[196:199], v178 offset:4096
	ds_read_b128 v[200:203], v178 offset:5120
	ds_read_b128 v[204:207], v178 offset:6144
	ds_read_b128 v[208:211], v178 offset:7168
	global_load_lds_dwordx4 v136, s[36:37]
	s_add_i32 m0, s45, 0xe000
	s_nop 0
	global_load_lds_dwordx4 v138, s[36:37]
	global_load_dwordx4 v[226:229], v223, s[100:101] nt
	s_add_u32 s84, s84, 1
	s_waitcnt vmcnt(9)
	s_waitcnt lgkmcnt(0)
	s_barrier
	s_setprio 1
	s_waitcnt lgkmcnt(0)
	v_mfma_i32_16x16x64_i8 v[124:127], v[140:143], v[180:183], v[124:127]
	v_mfma_i32_16x16x64_i8 v[120:123], v[148:151], v[180:183], v[120:123]
	v_mfma_i32_16x16x64_i8 v[116:119], v[140:143], v[188:191], v[116:119]
	v_mfma_i32_16x16x64_i8 v[112:115], v[148:151], v[188:191], v[112:115]
	v_mfma_i32_16x16x64_i8 v[104:107], v[140:143], v[196:199], v[104:107]
	v_mfma_i32_16x16x64_i8 v[96:99], v[148:151], v[196:199], v[96:99]
	v_mfma_i32_16x16x64_i8 v[88:91], v[140:143], v[204:207], v[88:91]
	v_mfma_i32_16x16x64_i8 v[80:83], v[148:151], v[204:207], v[80:83]
	v_mfma_i32_16x16x64_i8 v[124:127], v[144:147], v[184:187], v[124:127]
	v_mfma_i32_16x16x64_i8 v[120:123], v[152:155], v[184:187], v[120:123]
	v_mfma_i32_16x16x64_i8 v[116:119], v[144:147], v[192:195], v[116:119]
	v_mfma_i32_16x16x64_i8 v[112:115], v[152:155], v[192:195], v[112:115]
	v_mfma_i32_16x16x64_i8 v[104:107], v[144:147], v[200:203], v[104:107]
	v_mfma_i32_16x16x64_i8 v[96:99], v[152:155], v[200:203], v[96:99]
	v_mfma_i32_16x16x64_i8 v[88:91], v[144:147], v[208:211], v[88:91]
	v_mfma_i32_16x16x64_i8 v[80:83], v[152:155], v[208:211], v[80:83]
	s_setprio 0
	s_setprio 1
	v_mfma_i32_16x16x64_i8 v[108:111], v[156:159], v[180:183], v[108:111]
	v_mfma_i32_16x16x64_i8 v[100:103], v[164:167], v[180:183], v[100:103]
	v_mfma_i32_16x16x64_i8 v[92:95], v[156:159], v[188:191], v[92:95]
	v_mfma_i32_16x16x64_i8 v[84:87], v[164:167], v[188:191], v[84:87]
	v_mfma_i32_16x16x64_i8 v[76:79], v[156:159], v[196:199], v[76:79]
	v_mfma_i32_16x16x64_i8 v[72:75], v[164:167], v[196:199], v[72:75]
	v_mfma_i32_16x16x64_i8 v[68:71], v[156:159], v[204:207], v[68:71]
	v_mfma_i32_16x16x64_i8 v[64:67], v[164:167], v[204:207], v[64:67]
	v_mfma_i32_16x16x64_i8 v[108:111], v[160:163], v[184:187], v[108:111]
	v_mfma_i32_16x16x64_i8 v[100:103], v[168:171], v[184:187], v[100:103]
	v_mfma_i32_16x16x64_i8 v[92:95], v[160:163], v[192:195], v[92:95]
	v_mfma_i32_16x16x64_i8 v[84:87], v[168:171], v[192:195], v[84:87]
	v_mfma_i32_16x16x64_i8 v[76:79], v[160:163], v[200:203], v[76:79]
	v_mfma_i32_16x16x64_i8 v[72:75], v[168:171], v[200:203], v[72:75]
	v_mfma_i32_16x16x64_i8 v[68:71], v[160:163], v[208:211], v[68:71]
	v_mfma_i32_16x16x64_i8 v[64:67], v[168:171], v[208:211], v[64:67]
	s_setprio 0
	s_barrier
	s_add_i32 s75, s55, s42
	v_lshl_add_u64 v[172:173], s[38:39], 0, v[130:131]
	s_mov_b32 m0, s75
	ds_read_b128 v[180:183], v178 offset:16384
	ds_read_b128 v[184:187], v178 offset:17408
	ds_read_b128 v[188:191], v178 offset:18432
	ds_read_b128 v[192:195], v178 offset:19456
	ds_read_b128 v[196:199], v178 offset:20480
	ds_read_b128 v[200:203], v178 offset:21504
	ds_read_b128 v[204:207], v178 offset:22528
	ds_read_b128 v[208:211], v178 offset:23552
	global_load_lds_dwordx4 v130, s[38:39]
	s_add_i32 m0, s75, 0x2000
	s_add_u32 s76, s38, 0x80000
	v_lshl_add_u64 v[212:213], s[38:39], 0, v[134:135]
	s_addc_u32 s77, s39, 0
	s_add_i32 s75, s60, s42
	global_load_lds_dwordx4 v134, s[38:39]
	s_mov_b32 m0, s75
	v_lshl_add_u64 v[216:217], s[40:41], 0, v[132:133]
	global_load_lds_dwordx4 v130, s[76:77]
	s_add_i32 m0, s75, 0x2000
	s_nop 0
	global_load_lds_dwordx4 v134, s[76:77]
	v_lshl_add_u64 v[214:215], s[40:41], 0, v[128:129]
	s_mov_b32 m0, s45
	s_nop 0
	global_load_lds_dwordx4 v128, s[40:41]
	s_mov_b32 m0, s46
	s_nop 0
	global_load_lds_dwordx4 v132, s[40:41]
	s_waitcnt vmcnt(9)
	s_waitcnt lgkmcnt(0)
	s_barrier
	s_setprio 1
	s_waitcnt lgkmcnt(0)
	v_mfma_i32_16x16x64_i8 v[60:63], v[140:143], v[180:183], v[60:63]
	v_mfma_i32_16x16x64_i8 v[56:59], v[148:151], v[180:183], v[56:59]
	v_mfma_i32_16x16x64_i8 v[52:55], v[140:143], v[188:191], v[52:55]
	v_mfma_i32_16x16x64_i8 v[48:51], v[148:151], v[188:191], v[48:51]
	v_mfma_i32_16x16x64_i8 v[40:43], v[140:143], v[196:199], v[40:43]
	v_mfma_i32_16x16x64_i8 v[32:35], v[148:151], v[196:199], v[32:35]
	v_mfma_i32_16x16x64_i8 v[24:27], v[140:143], v[204:207], v[24:27]
	v_mfma_i32_16x16x64_i8 v[16:19], v[148:151], v[204:207], v[16:19]
	v_mfma_i32_16x16x64_i8 v[60:63], v[144:147], v[184:187], v[60:63]
	v_mfma_i32_16x16x64_i8 v[56:59], v[152:155], v[184:187], v[56:59]
	v_mfma_i32_16x16x64_i8 v[52:55], v[144:147], v[192:195], v[52:55]
	v_mfma_i32_16x16x64_i8 v[48:51], v[152:155], v[192:195], v[48:51]
	v_mfma_i32_16x16x64_i8 v[40:43], v[144:147], v[200:203], v[40:43]
	v_mfma_i32_16x16x64_i8 v[32:35], v[152:155], v[200:203], v[32:35]
	v_mfma_i32_16x16x64_i8 v[24:27], v[144:147], v[208:211], v[24:27]
	v_mfma_i32_16x16x64_i8 v[16:19], v[152:155], v[208:211], v[16:19]
	s_setprio 0
	s_setprio 1
	v_mfma_i32_16x16x64_i8 v[44:47], v[156:159], v[180:183], v[44:47]
	v_mfma_i32_16x16x64_i8 v[36:39], v[164:167], v[180:183], v[36:39]
	v_mfma_i32_16x16x64_i8 v[28:31], v[156:159], v[188:191], v[28:31]
	v_mfma_i32_16x16x64_i8 v[20:23], v[164:167], v[188:191], v[20:23]
	v_mfma_i32_16x16x64_i8 v[12:15], v[156:159], v[196:199], v[12:15]
	v_mfma_i32_16x16x64_i8 v[8:11], v[164:167], v[196:199], v[8:11]
	v_mfma_i32_16x16x64_i8 v[4:7], v[156:159], v[204:207], v[4:7]
	v_mfma_i32_16x16x64_i8 v[0:3], v[164:167], v[204:207], v[0:3]
	v_mfma_i32_16x16x64_i8 v[44:47], v[160:163], v[184:187], v[44:47]
	v_mfma_i32_16x16x64_i8 v[36:39], v[168:171], v[184:187], v[36:39]
	v_mfma_i32_16x16x64_i8 v[28:31], v[160:163], v[192:195], v[28:31]
	v_mfma_i32_16x16x64_i8 v[20:23], v[168:171], v[192:195], v[20:23]
	v_mfma_i32_16x16x64_i8 v[12:15], v[160:163], v[200:203], v[12:15]
	v_mfma_i32_16x16x64_i8 v[8:11], v[168:171], v[200:203], v[8:11]
	v_mfma_i32_16x16x64_i8 v[4:7], v[160:163], v[208:211], v[4:7]
	v_mfma_i32_16x16x64_i8 v[0:3], v[168:171], v[208:211], v[0:3]
	s_setprio 0
	s_barrier
	s_add_i32 s75, 0, 0x18000
	s_add_i32 s76, 0, 0x1c000
	ds_read_b128 v[140:143], v177 offset:32768
	ds_read_b128 v[144:147], v177 offset:33792
	ds_read_b128 v[148:151], v177 offset:34816
	ds_read_b128 v[152:155], v177 offset:35840
	ds_read_b128 v[156:159], v177 offset:49152
	ds_read_b128 v[160:163], v177 offset:50176
	ds_read_b128 v[164:167], v177 offset:51200
	ds_read_b128 v[168:171], v177 offset:52224
	s_add_u32 s40, s40, 0x80000
	s_addc_u32 s41, s41, 0
	s_mov_b32 m0, s47
	ds_read_b128 v[180:183], v178 offset:32768
	ds_read_b128 v[184:187], v178 offset:33792
	ds_read_b128 v[188:191], v178 offset:34816
	ds_read_b128 v[192:195], v178 offset:35840
	ds_read_b128 v[196:199], v178 offset:36864
	ds_read_b128 v[200:203], v178 offset:37888
	ds_read_b128 v[204:207], v178 offset:38912
	ds_read_b128 v[208:211], v178 offset:39936
	global_load_lds_dwordx4 v128, s[40:41]
	s_mov_b32 m0, s48
	s_nop 0
	global_load_lds_dwordx4 v132, s[40:41]
	s_waitcnt vmcnt(9)
	s_waitcnt lgkmcnt(0)
	s_barrier
	s_setprio 1
	s_waitcnt lgkmcnt(0)
	v_mfma_i32_16x16x64_i8 v[124:127], v[140:143], v[180:183], v[124:127]
	v_mfma_i32_16x16x64_i8 v[120:123], v[148:151], v[180:183], v[120:123]
	v_mfma_i32_16x16x64_i8 v[116:119], v[140:143], v[188:191], v[116:119]
	v_mfma_i32_16x16x64_i8 v[112:115], v[148:151], v[188:191], v[112:115]
	v_mfma_i32_16x16x64_i8 v[104:107], v[140:143], v[196:199], v[104:107]
	v_mfma_i32_16x16x64_i8 v[96:99], v[148:151], v[196:199], v[96:99]
	v_mfma_i32_16x16x64_i8 v[88:91], v[140:143], v[204:207], v[88:91]
	v_mfma_i32_16x16x64_i8 v[80:83], v[148:151], v[204:207], v[80:83]
	v_mfma_i32_16x16x64_i8 v[124:127], v[144:147], v[184:187], v[124:127]
	v_mfma_i32_16x16x64_i8 v[120:123], v[152:155], v[184:187], v[120:123]
	v_mfma_i32_16x16x64_i8 v[116:119], v[144:147], v[192:195], v[116:119]
	v_mfma_i32_16x16x64_i8 v[112:115], v[152:155], v[192:195], v[112:115]
	v_mfma_i32_16x16x64_i8 v[104:107], v[144:147], v[200:203], v[104:107]
	v_mfma_i32_16x16x64_i8 v[96:99], v[152:155], v[200:203], v[96:99]
	v_mfma_i32_16x16x64_i8 v[88:91], v[144:147], v[208:211], v[88:91]
	v_mfma_i32_16x16x64_i8 v[80:83], v[152:155], v[208:211], v[80:83]
	s_setprio 0
	s_setprio 1
	v_mfma_i32_16x16x64_i8 v[108:111], v[156:159], v[180:183], v[108:111]
	v_mfma_i32_16x16x64_i8 v[100:103], v[164:167], v[180:183], v[100:103]
	v_mfma_i32_16x16x64_i8 v[92:95], v[156:159], v[188:191], v[92:95]
	v_mfma_i32_16x16x64_i8 v[84:87], v[164:167], v[188:191], v[84:87]
	v_mfma_i32_16x16x64_i8 v[76:79], v[156:159], v[196:199], v[76:79]
	v_mfma_i32_16x16x64_i8 v[72:75], v[164:167], v[196:199], v[72:75]
	v_mfma_i32_16x16x64_i8 v[68:71], v[156:159], v[204:207], v[68:71]
	v_mfma_i32_16x16x64_i8 v[64:67], v[164:167], v[204:207], v[64:67]
	v_mfma_i32_16x16x64_i8 v[108:111], v[160:163], v[184:187], v[108:111]
	v_mfma_i32_16x16x64_i8 v[100:103], v[168:171], v[184:187], v[100:103]
	v_mfma_i32_16x16x64_i8 v[92:95], v[160:163], v[192:195], v[92:95]
	v_mfma_i32_16x16x64_i8 v[84:87], v[168:171], v[192:195], v[84:87]
	v_mfma_i32_16x16x64_i8 v[76:79], v[160:163], v[200:203], v[76:79]
	v_mfma_i32_16x16x64_i8 v[72:75], v[168:171], v[200:203], v[72:75]
	v_mfma_i32_16x16x64_i8 v[68:71], v[160:163], v[208:211], v[68:71]
	v_mfma_i32_16x16x64_i8 v[64:67], v[168:171], v[208:211], v[64:67]
	s_setprio 0
	s_barrier
	s_add_i32 s40, s75, s42
	v_lshl_add_u64 v[172:173], v[172:173], 0, s[20:21]
	s_mov_b32 m0, s40
	ds_read_b128 v[180:183], v178 offset:49152
	ds_read_b128 v[184:187], v178 offset:50176
	ds_read_b128 v[188:191], v178 offset:51200
	ds_read_b128 v[192:195], v178 offset:52224
	ds_read_b128 v[196:199], v178 offset:53248
	ds_read_b128 v[200:203], v178 offset:54272
	ds_read_b128 v[204:207], v178 offset:55296
	ds_read_b128 v[208:211], v178 offset:56320
	global_load_lds_dwordx4 v[172:173], off
	s_add_i32 m0, s40, 0x2000
	s_add_u32 s38, s38, 0x80080
	v_lshl_add_u64 v[172:173], v[212:213], 0, s[20:21]
	s_addc_u32 s39, s39, 0
	s_add_i32 s40, s76, s42
	global_load_lds_dwordx4 v[172:173], off
	s_mov_b32 m0, s40
	s_nop 0
	global_load_lds_dwordx4 v130, s[38:39]
	s_add_i32 m0, s40, 0x2000
	s_nop 0
	global_load_lds_dwordx4 v134, s[38:39]
	v_lshl_add_u64 v[172:173], v[214:215], 0, s[20:21]
	s_mov_b32 m0, s51
	s_nop 0
	global_load_lds_dwordx4 v[172:173], off
	v_lshl_add_u64 v[172:173], v[216:217], 0, s[20:21]
	s_mov_b32 m0, s52
	s_nop 0
	global_load_lds_dwordx4 v[172:173], off
	s_waitcnt vmcnt(8)
	s_waitcnt lgkmcnt(0)
	s_barrier
	s_setprio 1
	s_waitcnt lgkmcnt(0)
	v_mfma_i32_16x16x64_i8 v[60:63], v[140:143], v[180:183], v[60:63]
	v_mfma_i32_16x16x64_i8 v[56:59], v[148:151], v[180:183], v[56:59]
	v_mfma_i32_16x16x64_i8 v[52:55], v[140:143], v[188:191], v[52:55]
	v_fmaak_f32 v226, v226, v220, 0x4b400000
	v_mfma_i32_16x16x64_i8 v[48:51], v[148:151], v[188:191], v[48:51]
	v_mfma_i32_16x16x64_i8 v[40:43], v[140:143], v[196:199], v[40:43]
	v_mfma_i32_16x16x64_i8 v[32:35], v[148:151], v[196:199], v[32:35]
	v_fmaak_f32 v227, v227, v225, 0x4b400000
	v_mfma_i32_16x16x64_i8 v[24:27], v[140:143], v[204:207], v[24:27]
	v_mfma_i32_16x16x64_i8 v[16:19], v[148:151], v[204:207], v[16:19]
	v_mfma_i32_16x16x64_i8 v[60:63], v[144:147], v[184:187], v[60:63]
	v_fmaak_f32 v228, v228, v252, 0x4b400000
	v_mfma_i32_16x16x64_i8 v[56:59], v[152:155], v[184:187], v[56:59]
	v_mfma_i32_16x16x64_i8 v[52:55], v[144:147], v[192:195], v[52:55]
	v_mfma_i32_16x16x64_i8 v[48:51], v[152:155], v[192:195], v[48:51]
	v_fmaak_f32 v229, v229, v253, 0x4b400000
	v_mfma_i32_16x16x64_i8 v[40:43], v[144:147], v[200:203], v[40:43]
	v_mfma_i32_16x16x64_i8 v[32:35], v[152:155], v[200:203], v[32:35]
	v_mfma_i32_16x16x64_i8 v[24:27], v[144:147], v[208:211], v[24:27]
	v_alignbit_b32 v239, v226, v239, 8
	v_mfma_i32_16x16x64_i8 v[16:19], v[152:155], v[208:211], v[16:19]
	s_setprio 0
	s_setprio 1
	v_mfma_i32_16x16x64_i8 v[44:47], v[156:159], v[180:183], v[44:47]
	v_mfma_i32_16x16x64_i8 v[36:39], v[164:167], v[180:183], v[36:39]
	v_alignbit_b32 v243, v227, v243, 8
	v_mfma_i32_16x16x64_i8 v[28:31], v[156:159], v[188:191], v[28:31]
	v_mfma_i32_16x16x64_i8 v[20:23], v[164:167], v[188:191], v[20:23]
	v_mfma_i32_16x16x64_i8 v[12:15], v[156:159], v[196:199], v[12:15]
	v_alignbit_b32 v247, v228, v247, 8
	v_mfma_i32_16x16x64_i8 v[8:11], v[164:167], v[196:199], v[8:11]
	v_mfma_i32_16x16x64_i8 v[4:7], v[156:159], v[204:207], v[4:7]
	v_mfma_i32_16x16x64_i8 v[0:3], v[164:167], v[204:207], v[0:3]
	v_alignbit_b32 v251, v229, v251, 8
	v_mfma_i32_16x16x64_i8 v[44:47], v[160:163], v[184:187], v[44:47]
	v_mfma_i32_16x16x64_i8 v[36:39], v[168:171], v[184:187], v[36:39]
	v_mfma_i32_16x16x64_i8 v[28:31], v[160:163], v[192:195], v[28:31]
	v_add_u32_e32 v223, 0x4000, v223
	v_mfma_i32_16x16x64_i8 v[20:23], v[168:171], v[192:195], v[20:23]
	v_mfma_i32_16x16x64_i8 v[12:15], v[160:163], v[200:203], v[12:15]
	v_mfma_i32_16x16x64_i8 v[8:11], v[168:171], v[200:203], v[8:11]
	v_mfma_i32_16x16x64_i8 v[4:7], v[160:163], v[208:211], v[4:7]
	v_mfma_i32_16x16x64_i8 v[0:3], v[168:171], v[208:211], v[0:3]
	s_setprio 0
	s_barrier
	s_and_b32 s77, s84, 3
	s_cbranch_scc0 .Lq_mv_L

.Lq_body_ST:
	s_add_i32 s74, s38, 2
	s_add_u32 s39, s36, 0xfff80080
	s_addc_u32 s40, s37, -1
	s_cmp_eq_u32 s71, s38
	s_cselect_b32 s41, s67, s40
	s_cselect_b32 s40, s68, s39
	ds_read_b128 v[140:143], v177
	ds_read_b128 v[144:147], v177 offset:1024
	ds_read_b128 v[148:151], v177 offset:2048
	ds_read_b128 v[152:155], v177 offset:3072
	ds_read_b128 v[156:159], v177 offset:16384
	ds_read_b128 v[160:163], v177 offset:17408
	ds_read_b128 v[164:167], v177 offset:18432
	ds_read_b128 v[168:171], v177 offset:19456
	s_cselect_b32 s38, s70, s72
	s_cselect_b32 s39, s69, s73
	s_add_i32 m0, s45, 0xc000
	ds_read_b128 v[180:183], v178
	ds_read_b128 v[184:187], v178 offset:1024
	ds_read_b128 v[188:191], v178 offset:2048
	ds_read_b128 v[192:195], v178 offset:3072
	ds_read_b128 v[196:199], v178 offset:4096
	ds_read_b128 v[200:203], v178 offset:5120
	ds_read_b128 v[204:207], v178 offset:6144
	ds_read_b128 v[208:211], v178 offset:7168
	global_load_lds_dwordx4 v136, s[36:37]
	s_add_i32 m0, s45, 0xe000
	s_nop 0
	global_load_lds_dwordx4 v138, s[36:37]
	global_store_dwordx4 v224, v[236:239], s[98:99]
	s_add_u32 s98, s98, 0x2b00
	s_addc_u32 s99, s99, 0
	global_store_dwordx4 v224, v[240:243], s[98:99]
	s_add_u32 s98, s98, 0x2b00
	s_addc_u32 s99, s99, 0
	global_store_dwordx4 v224, v[244:247], s[98:99]
	s_add_u32 s98, s98, 0x2b00
	s_addc_u32 s99, s99, 0
	global_store_dwordx4 v224, v[248:251], s[98:99]
	v_subrev_u32_e32 v223, 0x40000, v223
	s_cmp_lt_u32 s84, s87
	s_cbranch_scc0 .Lq_st_last
	s_cmp_lt_u32 s84, s89
	s_cbranch_scc0 .Lq_st_full
	s_sub_u32 s98, s98, 0x8080
	s_subb_u32 s99, s99, 0
	s_add_u32 s100, s100, 0x200000
	s_addc_u32 s101, s101, 0

.Lq_st_j:
	s_waitcnt vmcnt(13)
	s_waitcnt lgkmcnt(0)
	s_barrier
	s_setprio 1
	s_waitcnt lgkmcnt(0)
	v_mfma_i32_16x16x64_i8 v[124:127], v[140:143], v[180:183], v[124:127]
	v_mfma_i32_16x16x64_i8 v[120:123], v[148:151], v[180:183], v[120:123]
	v_mfma_i32_16x16x64_i8 v[116:119], v[140:143], v[188:191], v[116:119]
	v_mfma_i32_16x16x64_i8 v[112:115], v[148:151], v[188:191], v[112:115]
	v_mfma_i32_16x16x64_i8 v[104:107], v[140:143], v[196:199], v[104:107]
	v_mfma_i32_16x16x64_i8 v[96:99], v[148:151], v[196:199], v[96:99]
	v_mfma_i32_16x16x64_i8 v[88:91], v[140:143], v[204:207], v[88:91]
	v_mfma_i32_16x16x64_i8 v[80:83], v[148:151], v[204:207], v[80:83]
	v_mfma_i32_16x16x64_i8 v[124:127], v[144:147], v[184:187], v[124:127]
	v_mfma_i32_16x16x64_i8 v[120:123], v[152:155], v[184:187], v[120:123]
	v_mfma_i32_16x16x64_i8 v[116:119], v[144:147], v[192:195], v[116:119]
	v_mfma_i32_16x16x64_i8 v[112:115], v[152:155], v[192:195], v[112:115]
	v_mfma_i32_16x16x64_i8 v[104:107], v[144:147], v[200:203], v[104:107]
	v_mfma_i32_16x16x64_i8 v[96:99], v[152:155], v[200:203], v[96:99]
	v_mfma_i32_16x16x64_i8 v[88:91], v[144:147], v[208:211], v[88:91]
	v_mfma_i32_16x16x64_i8 v[80:83], v[152:155], v[208:211], v[80:83]
	s_setprio 0
	s_setprio 1
	v_mfma_i32_16x16x64_i8 v[108:111], v[156:159], v[180:183], v[108:111]
	v_mfma_i32_16x16x64_i8 v[100:103], v[164:167], v[180:183], v[100:103]
	v_mfma_i32_16x16x64_i8 v[92:95], v[156:159], v[188:191], v[92:95]
	v_mfma_i32_16x16x64_i8 v[84:87], v[164:167], v[188:191], v[84:87]
	v_mfma_i32_16x16x64_i8 v[76:79], v[156:159], v[196:199], v[76:79]
	v_mfma_i32_16x16x64_i8 v[72:75], v[164:167], v[196:199], v[72:75]
	v_mfma_i32_16x16x64_i8 v[68:71], v[156:159], v[204:207], v[68:71]
	v_mfma_i32_16x16x64_i8 v[64:67], v[164:167], v[204:207], v[64:67]
	v_mfma_i32_16x16x64_i8 v[108:111], v[160:163], v[184:187], v[108:111]
	v_mfma_i32_16x16x64_i8 v[100:103], v[168:171], v[184:187], v[100:103]
	v_mfma_i32_16x16x64_i8 v[92:95], v[160:163], v[192:195], v[92:95]
	v_mfma_i32_16x16x64_i8 v[84:87], v[168:171], v[192:195], v[84:87]
	v_mfma_i32_16x16x64_i8 v[76:79], v[160:163], v[200:203], v[76:79]
	v_mfma_i32_16x16x64_i8 v[72:75], v[168:171], v[200:203], v[72:75]
	v_mfma_i32_16x16x64_i8 v[68:71], v[160:163], v[208:211], v[68:71]
	v_mfma_i32_16x16x64_i8 v[64:67], v[168:171], v[208:211], v[64:67]
	s_setprio 0
	s_barrier
	s_add_i32 s75, s55, s42
	v_lshl_add_u64 v[172:173], s[38:39], 0, v[130:131]
	s_mov_b32 m0, s75
	ds_read_b128 v[180:183], v178 offset:16384
	ds_read_b128 v[184:187], v178 offset:17408
	ds_read_b128 v[188:191], v178 offset:18432
	ds_read_b128 v[192:195], v178 offset:19456
	ds_read_b128 v[196:199], v178 offset:20480
	ds_read_b128 v[200:203], v178 offset:21504
	ds_read_b128 v[204:207], v178 offset:22528
	ds_read_b128 v[208:211], v178 offset:23552
	global_load_lds_dwordx4 v130, s[38:39]
	s_add_i32 m0, s75, 0x2000
	s_add_u32 s76, s38, 0x80000
	v_lshl_add_u64 v[212:213], s[38:39], 0, v[134:135]
	s_addc_u32 s77, s39, 0
	s_add_i32 s75, s60, s42
	global_load_lds_dwordx4 v134, s[38:39]
	s_mov_b32 m0, s75
	v_lshl_add_u64 v[216:217], s[40:41], 0, v[132:133]
	global_load_lds_dwordx4 v130, s[76:77]
	s_add_i32 m0, s75, 0x2000
	s_nop 0
	global_load_lds_dwordx4 v134, s[76:77]
	v_lshl_add_u64 v[214:215], s[40:41], 0, v[128:129]
	s_mov_b32 m0, s45
	s_nop 0
	global_load_lds_dwordx4 v128, s[40:41]
	s_mov_b32 m0, s46
	s_nop 0
	global_load_lds_dwordx4 v132, s[40:41]
	s_waitcnt vmcnt(13)
	s_waitcnt lgkmcnt(0)
	s_barrier
	s_setprio 1
	s_waitcnt lgkmcnt(0)
	v_mfma_i32_16x16x64_i8 v[60:63], v[140:143], v[180:183], v[60:63]
	v_mfma_i32_16x16x64_i8 v[56:59], v[148:151], v[180:183], v[56:59]
	v_mfma_i32_16x16x64_i8 v[52:55], v[140:143], v[188:191], v[52:55]
	v_mfma_i32_16x16x64_i8 v[48:51], v[148:151], v[188:191], v[48:51]
	v_mfma_i32_16x16x64_i8 v[40:43], v[140:143], v[196:199], v[40:43]
	v_mfma_i32_16x16x64_i8 v[32:35], v[148:151], v[196:199], v[32:35]
	v_mfma_i32_16x16x64_i8 v[24:27], v[140:143], v[204:207], v[24:27]
	v_mfma_i32_16x16x64_i8 v[16:19], v[148:151], v[204:207], v[16:19]
	v_mfma_i32_16x16x64_i8 v[60:63], v[144:147], v[184:187], v[60:63]
	v_mfma_i32_16x16x64_i8 v[56:59], v[152:155], v[184:187], v[56:59]
	v_mfma_i32_16x16x64_i8 v[52:55], v[144:147], v[192:195], v[52:55]
	v_mfma_i32_16x16x64_i8 v[48:51], v[152:155], v[192:195], v[48:51]
	v_mfma_i32_16x16x64_i8 v[40:43], v[144:147], v[200:203], v[40:43]
	v_mfma_i32_16x16x64_i8 v[32:35], v[152:155], v[200:203], v[32:35]
	v_mfma_i32_16x16x64_i8 v[24:27], v[144:147], v[208:211], v[24:27]
	v_mfma_i32_16x16x64_i8 v[16:19], v[152:155], v[208:211], v[16:19]
	s_setprio 0
	s_setprio 1
	v_mfma_i32_16x16x64_i8 v[44:47], v[156:159], v[180:183], v[44:47]
	v_mfma_i32_16x16x64_i8 v[36:39], v[164:167], v[180:183], v[36:39]
	v_mfma_i32_16x16x64_i8 v[28:31], v[156:159], v[188:191], v[28:31]
	v_mfma_i32_16x16x64_i8 v[20:23], v[164:167], v[188:191], v[20:23]
	v_mfma_i32_16x16x64_i8 v[12:15], v[156:159], v[196:199], v[12:15]
	v_mfma_i32_16x16x64_i8 v[8:11], v[164:167], v[196:199], v[8:11]
	v_mfma_i32_16x16x64_i8 v[4:7], v[156:159], v[204:207], v[4:7]
	v_mfma_i32_16x16x64_i8 v[0:3], v[164:167], v[204:207], v[0:3]
	v_mfma_i32_16x16x64_i8 v[44:47], v[160:163], v[184:187], v[44:47]
	v_mfma_i32_16x16x64_i8 v[36:39], v[168:171], v[184:187], v[36:39]
	v_mfma_i32_16x16x64_i8 v[28:31], v[160:163], v[192:195], v[28:31]
	v_mfma_i32_16x16x64_i8 v[20:23], v[168:171], v[192:195], v[20:23]
	v_mfma_i32_16x16x64_i8 v[12:15], v[160:163], v[200:203], v[12:15]
	v_mfma_i32_16x16x64_i8 v[8:11], v[168:171], v[200:203], v[8:11]
	v_mfma_i32_16x16x64_i8 v[4:7], v[160:163], v[208:211], v[4:7]
	v_mfma_i32_16x16x64_i8 v[0:3], v[168:171], v[208:211], v[0:3]
	s_setprio 0
	s_barrier
	s_add_i32 s75, 0, 0x18000
	s_add_i32 s76, 0, 0x1c000
	ds_read_b128 v[140:143], v177 offset:32768
	ds_read_b128 v[144:147], v177 offset:33792
	ds_read_b128 v[148:151], v177 offset:34816
	ds_read_b128 v[152:155], v177 offset:35840
	ds_read_b128 v[156:159], v177 offset:49152
	ds_read_b128 v[160:163], v177 offset:50176
	ds_read_b128 v[164:167], v177 offset:51200
	ds_read_b128 v[168:171], v177 offset:52224
	s_add_u32 s40, s40, 0x80000
	s_addc_u32 s41, s41, 0
	s_mov_b32 m0, s47
	ds_read_b128 v[180:183], v178 offset:32768
	ds_read_b128 v[184:187], v178 offset:33792
	ds_read_b128 v[188:191], v178 offset:34816
	ds_read_b128 v[192:195], v178 offset:35840
	ds_read_b128 v[196:199], v178 offset:36864
	ds_read_b128 v[200:203], v178 offset:37888
	ds_read_b128 v[204:207], v178 offset:38912
	ds_read_b128 v[208:211], v178 offset:39936
	global_load_lds_dwordx4 v128, s[40:41]
	s_mov_b32 m0, s48
	s_nop 0
	global_load_lds_dwordx4 v132, s[40:41]
	s_waitcnt vmcnt(13)
	s_waitcnt lgkmcnt(0)
	s_barrier
	s_setprio 1
	s_waitcnt lgkmcnt(0)
	v_mfma_i32_16x16x64_i8 v[124:127], v[140:143], v[180:183], v[124:127]
	v_mfma_i32_16x16x64_i8 v[120:123], v[148:151], v[180:183], v[120:123]
	v_mfma_i32_16x16x64_i8 v[116:119], v[140:143], v[188:191], v[116:119]
	v_mfma_i32_16x16x64_i8 v[112:115], v[148:151], v[188:191], v[112:115]
	v_mfma_i32_16x16x64_i8 v[104:107], v[140:143], v[196:199], v[104:107]
	v_mfma_i32_16x16x64_i8 v[96:99], v[148:151], v[196:199], v[96:99]
	v_mfma_i32_16x16x64_i8 v[88:91], v[140:143], v[204:207], v[88:91]
	v_mfma_i32_16x16x64_i8 v[80:83], v[148:151], v[204:207], v[80:83]
	v_mfma_i32_16x16x64_i8 v[124:127], v[144:147], v[184:187], v[124:127]
	v_mfma_i32_16x16x64_i8 v[120:123], v[152:155], v[184:187], v[120:123]
	v_mfma_i32_16x16x64_i8 v[116:119], v[144:147], v[192:195], v[116:119]
	v_mfma_i32_16x16x64_i8 v[112:115], v[152:155], v[192:195], v[112:115]
	v_mfma_i32_16x16x64_i8 v[104:107], v[144:147], v[200:203], v[104:107]
	v_mfma_i32_16x16x64_i8 v[96:99], v[152:155], v[200:203], v[96:99]
	v_mfma_i32_16x16x64_i8 v[88:91], v[144:147], v[208:211], v[88:91]
	v_mfma_i32_16x16x64_i8 v[80:83], v[152:155], v[208:211], v[80:83]
	s_setprio 0
	s_setprio 1
	v_mfma_i32_16x16x64_i8 v[108:111], v[156:159], v[180:183], v[108:111]
	v_mfma_i32_16x16x64_i8 v[100:103], v[164:167], v[180:183], v[100:103]
	v_mfma_i32_16x16x64_i8 v[92:95], v[156:159], v[188:191], v[92:95]
	v_mfma_i32_16x16x64_i8 v[84:87], v[164:167], v[188:191], v[84:87]
	v_mfma_i32_16x16x64_i8 v[76:79], v[156:159], v[196:199], v[76:79]
	v_mfma_i32_16x16x64_i8 v[72:75], v[164:167], v[196:199], v[72:75]
	v_mfma_i32_16x16x64_i8 v[68:71], v[156:159], v[204:207], v[68:71]
	v_mfma_i32_16x16x64_i8 v[64:67], v[164:167], v[204:207], v[64:67]
	v_mfma_i32_16x16x64_i8 v[108:111], v[160:163], v[184:187], v[108:111]
	v_mfma_i32_16x16x64_i8 v[100:103], v[168:171], v[184:187], v[100:103]
	v_mfma_i32_16x16x64_i8 v[92:95], v[160:163], v[192:195], v[92:95]
	v_mfma_i32_16x16x64_i8 v[84:87], v[168:171], v[192:195], v[84:87]
	v_mfma_i32_16x16x64_i8 v[76:79], v[160:163], v[200:203], v[76:79]
	v_mfma_i32_16x16x64_i8 v[72:75], v[168:171], v[200:203], v[72:75]
	v_mfma_i32_16x16x64_i8 v[68:71], v[160:163], v[208:211], v[68:71]
	v_mfma_i32_16x16x64_i8 v[64:67], v[168:171], v[208:211], v[64:67]
	s_setprio 0
	s_barrier
	s_add_i32 s40, s75, s42
	v_lshl_add_u64 v[172:173], v[172:173], 0, s[20:21]
	s_mov_b32 m0, s40
	ds_read_b128 v[180:183], v178 offset:49152
	ds_read_b128 v[184:187], v178 offset:50176
	ds_read_b128 v[188:191], v178 offset:51200
	ds_read_b128 v[192:195], v178 offset:52224
	ds_read_b128 v[196:199], v178 offset:53248
	ds_read_b128 v[200:203], v178 offset:54272
	ds_read_b128 v[204:207], v178 offset:55296
	ds_read_b128 v[208:211], v178 offset:56320
	global_load_lds_dwordx4 v[172:173], off
	s_add_i32 m0, s40, 0x2000
	s_add_u32 s38, s38, 0x80080
	v_lshl_add_u64 v[172:173], v[212:213], 0, s[20:21]
	s_addc_u32 s39, s39, 0
	s_add_i32 s40, s76, s42
	global_load_lds_dwordx4 v[172:173], off
	s_mov_b32 m0, s40
	s_nop 0
	global_load_lds_dwordx4 v130, s[38:39]
	s_add_i32 m0, s40, 0x2000
	s_nop 0
	global_load_lds_dwordx4 v134, s[38:39]
	v_lshl_add_u64 v[172:173], v[214:215], 0, s[20:21]
	s_mov_b32 m0, s51
	s_nop 0
	global_load_lds_dwordx4 v[172:173], off
	v_lshl_add_u64 v[172:173], v[216:217], 0, s[20:21]
	s_mov_b32 m0, s52
	s_nop 0
	global_load_lds_dwordx4 v[172:173], off
	s_waitcnt vmcnt(8)
	s_waitcnt lgkmcnt(0)
	s_barrier
	s_setprio 1
	s_waitcnt lgkmcnt(0)
	v_mfma_i32_16x16x64_i8 v[60:63], v[140:143], v[180:183], v[60:63]
	v_mfma_i32_16x16x64_i8 v[56:59], v[148:151], v[180:183], v[56:59]
	v_mfma_i32_16x16x64_i8 v[52:55], v[140:143], v[188:191], v[52:55]
	v_fmaak_f32 v226, v226, v220, 0x4b400000
	v_mfma_i32_16x16x64_i8 v[48:51], v[148:151], v[188:191], v[48:51]
	v_mfma_i32_16x16x64_i8 v[40:43], v[140:143], v[196:199], v[40:43]
	v_mfma_i32_16x16x64_i8 v[32:35], v[148:151], v[196:199], v[32:35]
	v_fmaak_f32 v227, v227, v225, 0x4b400000
	v_mfma_i32_16x16x64_i8 v[24:27], v[140:143], v[204:207], v[24:27]
	v_mfma_i32_16x16x64_i8 v[16:19], v[148:151], v[204:207], v[16:19]
	v_mfma_i32_16x16x64_i8 v[60:63], v[144:147], v[184:187], v[60:63]
	v_fmaak_f32 v228, v228, v252, 0x4b400000
	v_mfma_i32_16x16x64_i8 v[56:59], v[152:155], v[184:187], v[56:59]
	v_mfma_i32_16x16x64_i8 v[52:55], v[144:147], v[192:195], v[52:55]
	v_mfma_i32_16x16x64_i8 v[48:51], v[152:155], v[192:195], v[48:51]
	v_fmaak_f32 v229, v229, v253, 0x4b400000
	v_mfma_i32_16x16x64_i8 v[40:43], v[144:147], v[200:203], v[40:43]
	v_mfma_i32_16x16x64_i8 v[32:35], v[152:155], v[200:203], v[32:35]
	v_mfma_i32_16x16x64_i8 v[24:27], v[144:147], v[208:211], v[24:27]
	v_alignbit_b32 v239, v226, v239, 8
	v_mfma_i32_16x16x64_i8 v[16:19], v[152:155], v[208:211], v[16:19]
	s_setprio 0
	s_setprio 1
	v_mfma_i32_16x16x64_i8 v[44:47], v[156:159], v[180:183], v[44:47]
	v_mfma_i32_16x16x64_i8 v[36:39], v[164:167], v[180:183], v[36:39]
	v_alignbit_b32 v243, v227, v243, 8
	v_mfma_i32_16x16x64_i8 v[28:31], v[156:159], v[188:191], v[28:31]
	v_mfma_i32_16x16x64_i8 v[20:23], v[164:167], v[188:191], v[20:23]
	v_mfma_i32_16x16x64_i8 v[12:15], v[156:159], v[196:199], v[12:15]
	v_alignbit_b32 v247, v228, v247, 8
	v_mfma_i32_16x16x64_i8 v[8:11], v[164:167], v[196:199], v[8:11]
	v_mfma_i32_16x16x64_i8 v[4:7], v[156:159], v[204:207], v[4:7]
	v_mfma_i32_16x16x64_i8 v[0:3], v[164:167], v[204:207], v[0:3]
	v_alignbit_b32 v251, v229, v251, 8
	v_mfma_i32_16x16x64_i8 v[44:47], v[160:163], v[184:187], v[44:47]
	v_mfma_i32_16x16x64_i8 v[36:39], v[168:171], v[184:187], v[36:39]
	v_mfma_i32_16x16x64_i8 v[28:31], v[160:163], v[192:195], v[28:31]
	v_add_u32_e32 v223, 0x4000, v223
	v_mfma_i32_16x16x64_i8 v[20:23], v[168:171], v[192:195], v[20:23]
	v_mfma_i32_16x16x64_i8 v[12:15], v[160:163], v[200:203], v[12:15]
	v_mfma_i32_16x16x64_i8 v[8:11], v[168:171], v[200:203], v[8:11]
	v_mfma_i32_16x16x64_i8 v[4:7], v[160:163], v[208:211], v[4:7]
	v_mfma_i32_16x16x64_i8 v[0:3], v[168:171], v[208:211], v[0:3]
	s_setprio 0
	s_barrier
	s_cmp_eq_u32 s32, 0
	s_cbranch_scc1 .Lq_mvx_ST
	s_and_b32 s77, s84, 3
	s_cbranch_scc0 .Lq_mv_ST

.LBB0_1450:
	s_add_u32 s14, s96, 0xb0000
	s_addc_u32 s15, s97, 0
	s_add_u32 s16, s96, 0xc0000
	s_addc_u32 s17, s97, 0
	s_lshl_b32 s18, s18, 5
	s_and_b32 s63, s18, 0x60
	s_mov_b64 s[18:19], 0x80
	s_add_i32 m0, s54, 0x18000
	v_lshl_add_u64 v[6:7], v[6:7], 0, s[18:19]
	s_lshl_b32 s62, s9, 6
	s_lshl_b32 s9, s9, 13
	s_lshl_b32 s21, s63, 7
	s_waitcnt vmcnt(2)
	s_barrier
	global_load_lds_dwordx4 v[6:7], off
	v_lshl_add_u64 v[4:5], v[4:5], 0, s[18:19]
	s_add_i32 m0, s54, 0x1a000
	s_add_i32 s64, s54, 0x8000
	s_add_i32 s65, s54, 0xa000
	global_load_lds_dwordx4 v[4:5], off
	v_lshl_add_u64 v[0:1], v[0:1], 0, s[18:19]
	s_mov_b32 m0, s64
	s_add_u32 s24, s46, 0x158080
	global_load_lds_dwordx4 v[0:1], off
	v_lshl_add_u64 v[0:1], v[2:3], 0, s[18:19]
	s_mov_b32 m0, s65
	s_addc_u32 s25, s47, 0
	global_load_lds_dwordx4 v[0:1], off
	s_add_i32 m0, s54, 0x1c000
	v_lshl_add_u64 v[0:1], s[24:25], 0, v[130:131]
	global_load_lds_dwordx4 v[0:1], off
	v_lshl_add_u64 v[0:1], s[24:25], 0, v[134:135]
	s_add_i32 m0, s54, 0x1e000
	v_bfe_u32 v183, v235, 4, 2
	global_load_lds_dwordx4 v[0:1], off
	v_and_b32_e32 v182, 15, v235
	v_lshlrev_b32_e32 v0, 4, v183
	v_lshlrev_b32_e32 v1, 2, v235
	v_lshl_or_b32 v0, v182, 6, v0
	v_and_b32_e32 v1, 32, v1
	v_bitop3_b32 v2, v0, s9, v1 bitop3:0xde
	v_bitop3_b32 v184, v0, s21, v1 bitop3:0xde
	v_add_u32_e32 v184, 0x10000, v184
	v_lshrrev_b32_e32 v1, 1, v8
	v_mul_lo_u32 v0, v10, s8
	s_mov_b32 s9, 0x15800
	v_mad_u64_u32 v[0:1], s[26:27], v1, s9, v[0:1]
	v_or_b32_e32 v0, v0, v9
	s_mov_b64 s[24:25], 0x158080
	v_add_lshl_u32 v0, v0, v11, 1
	v_mov_b32_e32 v1, v131
	v_lshl_add_u64 v[136:137], v[0:1], 0, s[24:25]
	v_lshrrev_b32_e32 v1, 1, v12
	v_mul_lo_u32 v0, v13, s8
	v_mad_u64_u32 v[0:1], s[8:9], v1, s9, v[0:1]
	s_waitcnt vmcnt(6)
	v_or_b32_e32 v0, v0, v14
	s_cmpk_lt_u32 s20, 0x100
	v_add_lshl_u32 v0, v0, v15, 1
	v_mov_b32_e32 v1, v131
	s_cselect_b64 s[20:21], -1, 0
	v_lshl_add_u64 v[138:139], v[0:1], 0, s[24:25]
	v_mov_b32_e32 v185, s52
	s_add_i32 s66, 0, 0x10000
	s_add_i32 s67, 0, 0x14000
	v_add_u32_e32 v186, 0, v2
	s_mov_b32 s22, 0x38820610
	s_mov_b64 s[24:25], 0x20000
	s_mov_b64 s[26:27], 0x40000
	s_mov_b64 s[28:29], 0x60000
	s_mov_b64 s[30:31], 0x100000
	s_mov_b64 s[34:35], 0x120000
	s_mov_b64 s[36:37], 0x140000
	s_mov_b64 s[38:39], 0x160000
	s_mov_b32 s68, 0
	s_barrier
	s_branch .LBB0_1453

.LBB0_1474:
	s_add_i32 s75, s48, 2
	s_add_u32 s46, s44, 0x100
	s_addc_u32 s47, s45, 0
	s_cmp_eq_u32 s72, s48
	s_cselect_b32 s51, s41, s47
	s_cselect_b32 s50, s40, s46
	ds_read_b128 v[140:143], v184
	ds_read_b128 v[144:147], v184 offset:1024
	ds_read_b128 v[148:151], v184 offset:2048
	ds_read_b128 v[152:155], v184 offset:3072
	ds_read_b128 v[156:159], v184 offset:16384
	ds_read_b128 v[160:163], v184 offset:17408
	ds_read_b128 v[164:167], v184 offset:18432
	ds_read_b128 v[168:171], v184 offset:19456
	s_cselect_b32 s48, s42, s73
	s_cselect_b32 s49, s43, s74
	s_add_i32 m0, s54, 0xc000
	ds_read_b128 v[172:175], v186
	ds_read_b128 v[176:179], v186 offset:1024
	ds_read_b128 v[188:191], v186 offset:2048
	ds_read_b128 v[192:195], v186 offset:3072
	ds_read_b128 v[196:199], v186 offset:4096
	ds_read_b128 v[200:203], v186 offset:5120
	ds_read_b128 v[204:207], v186 offset:6144
	ds_read_b128 v[208:211], v186 offset:7168
	global_load_lds_dwordx4 v136, s[44:45]
	s_add_i32 m0, s54, 0xe000
	s_nop 0
	global_load_lds_dwordx4 v138, s[44:45]
	s_waitcnt vmcnt(8)
	s_waitcnt lgkmcnt(0)
	s_barrier
	s_setprio 1
	s_waitcnt lgkmcnt(0)
	v_mfma_i32_16x16x64_i8 v[124:127], v[140:143], v[172:175], v[124:127]
	v_mfma_i32_16x16x64_i8 v[120:123], v[148:151], v[172:175], v[120:123]
	v_mfma_i32_16x16x64_i8 v[116:119], v[140:143], v[188:191], v[116:119]
	v_mfma_i32_16x16x64_i8 v[112:115], v[148:151], v[188:191], v[112:115]
	v_mfma_i32_16x16x64_i8 v[104:107], v[140:143], v[196:199], v[104:107]
	v_mfma_i32_16x16x64_i8 v[96:99], v[148:151], v[196:199], v[96:99]
	v_mfma_i32_16x16x64_i8 v[88:91], v[140:143], v[204:207], v[88:91]
	v_mfma_i32_16x16x64_i8 v[80:83], v[148:151], v[204:207], v[80:83]
	v_mfma_i32_16x16x64_i8 v[124:127], v[144:147], v[176:179], v[124:127]
	v_mfma_i32_16x16x64_i8 v[120:123], v[152:155], v[176:179], v[120:123]
	v_mfma_i32_16x16x64_i8 v[116:119], v[144:147], v[192:195], v[116:119]
	v_mfma_i32_16x16x64_i8 v[112:115], v[152:155], v[192:195], v[112:115]
	v_mfma_i32_16x16x64_i8 v[104:107], v[144:147], v[200:203], v[104:107]
	v_mfma_i32_16x16x64_i8 v[96:99], v[152:155], v[200:203], v[96:99]
	v_mfma_i32_16x16x64_i8 v[88:91], v[144:147], v[208:211], v[88:91]
	v_mfma_i32_16x16x64_i8 v[80:83], v[152:155], v[208:211], v[80:83]
	s_setprio 0
	s_setprio 1
	v_mfma_i32_16x16x64_i8 v[108:111], v[156:159], v[172:175], v[108:111]
	v_mfma_i32_16x16x64_i8 v[100:103], v[164:167], v[172:175], v[100:103]
	v_mfma_i32_16x16x64_i8 v[92:95], v[156:159], v[188:191], v[92:95]
	v_mfma_i32_16x16x64_i8 v[84:87], v[164:167], v[188:191], v[84:87]
	v_mfma_i32_16x16x64_i8 v[76:79], v[156:159], v[196:199], v[76:79]
	v_mfma_i32_16x16x64_i8 v[72:75], v[164:167], v[196:199], v[72:75]
	v_mfma_i32_16x16x64_i8 v[68:71], v[156:159], v[204:207], v[68:71]
	v_mfma_i32_16x16x64_i8 v[64:67], v[164:167], v[204:207], v[64:67]
	v_mfma_i32_16x16x64_i8 v[108:111], v[160:163], v[176:179], v[108:111]
	v_mfma_i32_16x16x64_i8 v[100:103], v[168:171], v[176:179], v[100:103]
	v_mfma_i32_16x16x64_i8 v[92:95], v[160:163], v[192:195], v[92:95]
	v_mfma_i32_16x16x64_i8 v[84:87], v[168:171], v[192:195], v[84:87]
	v_mfma_i32_16x16x64_i8 v[76:79], v[160:163], v[200:203], v[76:79]
	v_mfma_i32_16x16x64_i8 v[72:75], v[168:171], v[200:203], v[72:75]
	v_mfma_i32_16x16x64_i8 v[68:71], v[160:163], v[208:211], v[68:71]
	v_mfma_i32_16x16x64_i8 v[64:67], v[168:171], v[208:211], v[64:67]
	s_setprio 0
	s_barrier
	s_add_i32 s44, s66, s53
	s_mov_b32 m0, s44
	ds_read_b128 v[172:175], v186 offset:16384
	ds_read_b128 v[176:179], v186 offset:17408
	ds_read_b128 v[188:191], v186 offset:18432
	ds_read_b128 v[192:195], v186 offset:19456
	ds_read_b128 v[196:199], v186 offset:20480
	ds_read_b128 v[200:203], v186 offset:21504
	ds_read_b128 v[204:207], v186 offset:22528
	ds_read_b128 v[208:211], v186 offset:23552
	global_load_lds_dwordx4 v130, s[48:49]
	s_add_i32 m0, s44, 0x2000
	s_add_u32 s44, s48, 0x158000
	s_addc_u32 s45, s49, 0
	s_add_i32 s76, s67, s53
	global_load_lds_dwordx4 v134, s[48:49]
	s_mov_b32 m0, s76
	s_nop 0
	global_load_lds_dwordx4 v130, s[44:45]
	s_add_i32 m0, s76, 0x2000
	s_nop 0
	global_load_lds_dwordx4 v134, s[44:45]
	s_mov_b32 m0, s54
	s_nop 0
	global_load_lds_dwordx4 v128, s[50:51]
	s_mov_b32 m0, s55
	s_nop 0
	global_load_lds_dwordx4 v132, s[50:51]
	s_waitcnt vmcnt(8)
	s_waitcnt lgkmcnt(0)
	s_barrier
	s_setprio 1
	s_waitcnt lgkmcnt(0)
	v_mfma_i32_16x16x64_i8 v[60:63], v[140:143], v[172:175], v[60:63]
	v_mfma_i32_16x16x64_i8 v[56:59], v[148:151], v[172:175], v[56:59]
	v_mfma_i32_16x16x64_i8 v[52:55], v[140:143], v[188:191], v[52:55]
	v_mfma_i32_16x16x64_i8 v[48:51], v[148:151], v[188:191], v[48:51]
	v_mfma_i32_16x16x64_i8 v[40:43], v[140:143], v[196:199], v[40:43]
	v_mfma_i32_16x16x64_i8 v[32:35], v[148:151], v[196:199], v[32:35]
	v_mfma_i32_16x16x64_i8 v[24:27], v[140:143], v[204:207], v[24:27]
	v_mfma_i32_16x16x64_i8 v[16:19], v[148:151], v[204:207], v[16:19]
	v_mfma_i32_16x16x64_i8 v[60:63], v[144:147], v[176:179], v[60:63]
	v_mfma_i32_16x16x64_i8 v[56:59], v[152:155], v[176:179], v[56:59]
	v_mfma_i32_16x16x64_i8 v[52:55], v[144:147], v[192:195], v[52:55]
	v_mfma_i32_16x16x64_i8 v[48:51], v[152:155], v[192:195], v[48:51]
	v_mfma_i32_16x16x64_i8 v[40:43], v[144:147], v[200:203], v[40:43]
	v_mfma_i32_16x16x64_i8 v[32:35], v[152:155], v[200:203], v[32:35]
	v_mfma_i32_16x16x64_i8 v[24:27], v[144:147], v[208:211], v[24:27]
	v_mfma_i32_16x16x64_i8 v[16:19], v[152:155], v[208:211], v[16:19]
	s_setprio 0
	s_setprio 1
	v_mfma_i32_16x16x64_i8 v[44:47], v[156:159], v[172:175], v[44:47]
	v_mfma_i32_16x16x64_i8 v[36:39], v[164:167], v[172:175], v[36:39]
	v_mfma_i32_16x16x64_i8 v[28:31], v[156:159], v[188:191], v[28:31]
	v_mfma_i32_16x16x64_i8 v[20:23], v[164:167], v[188:191], v[20:23]
	v_mfma_i32_16x16x64_i8 v[12:15], v[156:159], v[196:199], v[12:15]
	v_mfma_i32_16x16x64_i8 v[8:11], v[164:167], v[196:199], v[8:11]
	v_mfma_i32_16x16x64_i8 v[4:7], v[156:159], v[204:207], v[4:7]
	v_mfma_i32_16x16x64_i8 v[0:3], v[164:167], v[204:207], v[0:3]
	v_mfma_i32_16x16x64_i8 v[44:47], v[160:163], v[176:179], v[44:47]
	v_mfma_i32_16x16x64_i8 v[36:39], v[168:171], v[176:179], v[36:39]
	v_mfma_i32_16x16x64_i8 v[28:31], v[160:163], v[192:195], v[28:31]
	v_mfma_i32_16x16x64_i8 v[20:23], v[168:171], v[192:195], v[20:23]
	v_mfma_i32_16x16x64_i8 v[12:15], v[160:163], v[200:203], v[12:15]
	v_mfma_i32_16x16x64_i8 v[8:11], v[168:171], v[200:203], v[8:11]
	v_mfma_i32_16x16x64_i8 v[4:7], v[160:163], v[208:211], v[4:7]
	v_mfma_i32_16x16x64_i8 v[0:3], v[168:171], v[208:211], v[0:3]
	s_setprio 0
	s_barrier
	s_add_i32 s76, 0, 0x18000
	s_add_i32 s77, 0, 0x1c000
	ds_read_b128 v[140:143], v184 offset:32768
	ds_read_b128 v[144:147], v184 offset:33792
	ds_read_b128 v[148:151], v184 offset:34816
	ds_read_b128 v[152:155], v184 offset:35840
	ds_read_b128 v[156:159], v184 offset:49152
	ds_read_b128 v[160:163], v184 offset:50176
	ds_read_b128 v[164:167], v184 offset:51200
	ds_read_b128 v[168:171], v184 offset:52224
	s_add_u32 s44, s50, 0x158000
	s_addc_u32 s45, s51, 0
	s_mov_b32 m0, s60
	ds_read_b128 v[172:175], v186 offset:32768
	ds_read_b128 v[176:179], v186 offset:33792
	ds_read_b128 v[188:191], v186 offset:34816
	ds_read_b128 v[192:195], v186 offset:35840
	ds_read_b128 v[196:199], v186 offset:36864
	ds_read_b128 v[200:203], v186 offset:37888
	ds_read_b128 v[204:207], v186 offset:38912
	ds_read_b128 v[208:211], v186 offset:39936
	global_load_lds_dwordx4 v128, s[44:45]
	s_mov_b32 m0, s61
	s_nop 0
	global_load_lds_dwordx4 v132, s[44:45]
	s_waitcnt vmcnt(8)
	s_waitcnt lgkmcnt(0)
	s_barrier
	s_setprio 1
	s_waitcnt lgkmcnt(0)
	v_mfma_i32_16x16x64_i8 v[124:127], v[140:143], v[172:175], v[124:127]
	v_mfma_i32_16x16x64_i8 v[120:123], v[148:151], v[172:175], v[120:123]
	v_mfma_i32_16x16x64_i8 v[116:119], v[140:143], v[188:191], v[116:119]
	v_mfma_i32_16x16x64_i8 v[112:115], v[148:151], v[188:191], v[112:115]
	v_mfma_i32_16x16x64_i8 v[104:107], v[140:143], v[196:199], v[104:107]
	v_mfma_i32_16x16x64_i8 v[96:99], v[148:151], v[196:199], v[96:99]
	v_mfma_i32_16x16x64_i8 v[88:91], v[140:143], v[204:207], v[88:91]
	v_mfma_i32_16x16x64_i8 v[80:83], v[148:151], v[204:207], v[80:83]
	v_mfma_i32_16x16x64_i8 v[124:127], v[144:147], v[176:179], v[124:127]
	v_mfma_i32_16x16x64_i8 v[120:123], v[152:155], v[176:179], v[120:123]
	v_mfma_i32_16x16x64_i8 v[116:119], v[144:147], v[192:195], v[116:119]
	v_mfma_i32_16x16x64_i8 v[112:115], v[152:155], v[192:195], v[112:115]
	v_mfma_i32_16x16x64_i8 v[104:107], v[144:147], v[200:203], v[104:107]
	v_mfma_i32_16x16x64_i8 v[96:99], v[152:155], v[200:203], v[96:99]
	v_mfma_i32_16x16x64_i8 v[88:91], v[144:147], v[208:211], v[88:91]
	v_mfma_i32_16x16x64_i8 v[80:83], v[152:155], v[208:211], v[80:83]
	s_setprio 0
	s_setprio 1
	v_mfma_i32_16x16x64_i8 v[108:111], v[156:159], v[172:175], v[108:111]
	v_mfma_i32_16x16x64_i8 v[100:103], v[164:167], v[172:175], v[100:103]
	v_mfma_i32_16x16x64_i8 v[92:95], v[156:159], v[188:191], v[92:95]
	v_mfma_i32_16x16x64_i8 v[84:87], v[164:167], v[188:191], v[84:87]
	v_mfma_i32_16x16x64_i8 v[76:79], v[156:159], v[196:199], v[76:79]
	v_mfma_i32_16x16x64_i8 v[72:75], v[164:167], v[196:199], v[72:75]
	v_mfma_i32_16x16x64_i8 v[68:71], v[156:159], v[204:207], v[68:71]
	v_mfma_i32_16x16x64_i8 v[64:67], v[164:167], v[204:207], v[64:67]
	v_mfma_i32_16x16x64_i8 v[108:111], v[160:163], v[176:179], v[108:111]
	v_mfma_i32_16x16x64_i8 v[100:103], v[168:171], v[176:179], v[100:103]
	v_mfma_i32_16x16x64_i8 v[92:95], v[160:163], v[192:195], v[92:95]
	v_mfma_i32_16x16x64_i8 v[84:87], v[168:171], v[192:195], v[84:87]
	v_mfma_i32_16x16x64_i8 v[76:79], v[160:163], v[200:203], v[76:79]
	v_mfma_i32_16x16x64_i8 v[72:75], v[168:171], v[200:203], v[72:75]
	v_mfma_i32_16x16x64_i8 v[68:71], v[160:163], v[208:211], v[68:71]
	v_mfma_i32_16x16x64_i8 v[64:67], v[168:171], v[208:211], v[64:67]
	s_setprio 0
	s_barrier
	s_add_u32 s98, s48, s18
	s_addc_u32 s99, s49, s19
	s_add_u32 s100, s50, s18
	s_addc_u32 s101, s51, s19
	s_add_i32 s44, s76, s53
	s_mov_b32 m0, s44
	ds_read_b128 v[172:175], v186 offset:49152
	ds_read_b128 v[176:179], v186 offset:50176
	ds_read_b128 v[188:191], v186 offset:51200
	ds_read_b128 v[192:195], v186 offset:52224
	ds_read_b128 v[196:199], v186 offset:53248
	ds_read_b128 v[200:203], v186 offset:54272
	ds_read_b128 v[204:207], v186 offset:55296
	ds_read_b128 v[208:211], v186 offset:56320
	global_load_lds_dwordx4 v130, s[98:99]
	s_add_i32 m0, s44, 0x2000
	s_add_u32 s44, s48, 0x158080
	s_addc_u32 s45, s49, 0
	s_add_i32 s48, s77, s53
	global_load_lds_dwordx4 v134, s[98:99]
	s_mov_b32 m0, s48
	s_nop 0
	global_load_lds_dwordx4 v130, s[44:45]
	s_add_i32 m0, s48, 0x2000
	s_nop 0
	global_load_lds_dwordx4 v134, s[44:45]
	s_mov_b32 m0, s64
	s_nop 0
	global_load_lds_dwordx4 v128, s[100:101]
	s_mov_b32 m0, s65
	s_nop 0
	global_load_lds_dwordx4 v132, s[100:101]
	s_waitcnt vmcnt(8)
	s_waitcnt lgkmcnt(0)
	s_barrier
	s_setprio 1
	s_waitcnt lgkmcnt(0)
	v_mfma_i32_16x16x64_i8 v[60:63], v[140:143], v[172:175], v[60:63]
	v_mfma_i32_16x16x64_i8 v[56:59], v[148:151], v[172:175], v[56:59]
	v_mfma_i32_16x16x64_i8 v[52:55], v[140:143], v[188:191], v[52:55]
	v_mfma_i32_16x16x64_i8 v[48:51], v[148:151], v[188:191], v[48:51]
	v_mfma_i32_16x16x64_i8 v[40:43], v[140:143], v[196:199], v[40:43]
	v_mfma_i32_16x16x64_i8 v[32:35], v[148:151], v[196:199], v[32:35]
	v_mfma_i32_16x16x64_i8 v[24:27], v[140:143], v[204:207], v[24:27]
	v_mfma_i32_16x16x64_i8 v[16:19], v[148:151], v[204:207], v[16:19]
	v_mfma_i32_16x16x64_i8 v[60:63], v[144:147], v[176:179], v[60:63]
	v_mfma_i32_16x16x64_i8 v[56:59], v[152:155], v[176:179], v[56:59]
	v_mfma_i32_16x16x64_i8 v[52:55], v[144:147], v[192:195], v[52:55]
	v_mfma_i32_16x16x64_i8 v[48:51], v[152:155], v[192:195], v[48:51]
	v_mfma_i32_16x16x64_i8 v[40:43], v[144:147], v[200:203], v[40:43]
	v_mfma_i32_16x16x64_i8 v[32:35], v[152:155], v[200:203], v[32:35]
	v_mfma_i32_16x16x64_i8 v[24:27], v[144:147], v[208:211], v[24:27]
	v_mfma_i32_16x16x64_i8 v[16:19], v[152:155], v[208:211], v[16:19]
	s_setprio 0
	s_setprio 1
	v_mfma_i32_16x16x64_i8 v[44:47], v[156:159], v[172:175], v[44:47]
	v_mfma_i32_16x16x64_i8 v[36:39], v[164:167], v[172:175], v[36:39]
	v_mfma_i32_16x16x64_i8 v[28:31], v[156:159], v[188:191], v[28:31]
	v_mfma_i32_16x16x64_i8 v[20:23], v[164:167], v[188:191], v[20:23]
	v_mfma_i32_16x16x64_i8 v[12:15], v[156:159], v[196:199], v[12:15]
	v_mfma_i32_16x16x64_i8 v[8:11], v[164:167], v[196:199], v[8:11]
	v_mfma_i32_16x16x64_i8 v[4:7], v[156:159], v[204:207], v[4:7]
	v_mfma_i32_16x16x64_i8 v[0:3], v[164:167], v[204:207], v[0:3]
	v_mfma_i32_16x16x64_i8 v[44:47], v[160:163], v[176:179], v[44:47]
	v_mfma_i32_16x16x64_i8 v[36:39], v[168:171], v[176:179], v[36:39]
	v_mfma_i32_16x16x64_i8 v[28:31], v[160:163], v[192:195], v[28:31]
	v_mfma_i32_16x16x64_i8 v[20:23], v[168:171], v[192:195], v[20:23]
	v_mfma_i32_16x16x64_i8 v[12:15], v[160:163], v[200:203], v[12:15]
	v_mfma_i32_16x16x64_i8 v[8:11], v[168:171], v[200:203], v[8:11]
	v_mfma_i32_16x16x64_i8 v[4:7], v[160:163], v[208:211], v[4:7]
	v_mfma_i32_16x16x64_i8 v[0:3], v[168:171], v[208:211], v[0:3]
	s_setprio 0
	s_barrier
	s_add_u32 s73, s73, 0x100
	s_addc_u32 s74, s74, 0
	s_cmp_ge_i32 s75, s71
	s_mov_b64 s[44:45], s[46:47]
	s_mov_b32 s48, s75
	s_cbranch_scc0 .LBB0_1474
	v_cvt_f32_i32_e32 v140, v124
	v_cvt_f32_i32_e32 v141, v125
	v_cvt_f32_i32_e32 v124, v126
	v_cvt_f32_i32_e32 v125, v127
	v_cvt_f32_i32_e32 v142, v120
	v_cvt_f32_i32_e32 v143, v121
	v_cvt_f32_i32_e32 v126, v122
	v_cvt_f32_i32_e32 v127, v123
	v_cvt_f32_i32_e32 v146, v108
	v_cvt_f32_i32_e32 v147, v109
	v_cvt_f32_i32_e32 v120, v110
	v_cvt_f32_i32_e32 v121, v111
	v_cvt_f32_i32_e32 v148, v100
	v_cvt_f32_i32_e32 v149, v101
	v_cvt_f32_i32_e32 v122, v102
	v_cvt_f32_i32_e32 v123, v103
	v_cvt_f32_i32_e32 v144, v116
	v_cvt_f32_i32_e32 v145, v117
	v_cvt_f32_i32_e32 v116, v118
	v_cvt_f32_i32_e32 v117, v119
	v_cvt_f32_i32_e32 v118, v112
	v_cvt_f32_i32_e32 v119, v113
	v_cvt_f32_i32_e32 v112, v114
	v_cvt_f32_i32_e32 v113, v115
	v_cvt_f32_i32_e32 v152, v92
	v_cvt_f32_i32_e32 v153, v93
	v_cvt_f32_i32_e32 v100, v94
	v_cvt_f32_i32_e32 v101, v95
	v_cvt_f32_i32_e32 v156, v84
	v_cvt_f32_i32_e32 v157, v85
	v_cvt_f32_i32_e32 v102, v86
	v_cvt_f32_i32_e32 v103, v87
	v_cvt_f32_i32_e32 v114, v104
	v_cvt_f32_i32_e32 v115, v105
	v_cvt_f32_i32_e32 v86, v106
	v_cvt_f32_i32_e32 v87, v107
	v_cvt_f32_i32_e32 v150, v96
	v_cvt_f32_i32_e32 v151, v97
	v_cvt_f32_i32_e32 v92, v98
	v_cvt_f32_i32_e32 v93, v99
	v_cvt_f32_i32_e32 v160, v76
	v_cvt_f32_i32_e32 v161, v77
	v_cvt_f32_i32_e32 v84, v78
	v_cvt_f32_i32_e32 v85, v79
	v_cvt_f32_i32_e32 v162, v72
	v_cvt_f32_i32_e32 v163, v73
	v_cvt_f32_i32_e32 v94, v74
	v_cvt_f32_i32_e32 v95, v75
	v_cvt_f32_i32_e32 v154, v88
	v_cvt_f32_i32_e32 v155, v89
	v_cvt_f32_i32_e32 v78, v90
	v_cvt_f32_i32_e32 v79, v91
	v_cvt_f32_i32_e32 v158, v80
	v_cvt_f32_i32_e32 v159, v81
	v_cvt_f32_i32_e32 v80, v82
	v_cvt_f32_i32_e32 v81, v83
	v_cvt_f32_i32_e32 v164, v68
	v_cvt_f32_i32_e32 v165, v69
	v_cvt_f32_i32_e32 v76, v70
	v_cvt_f32_i32_e32 v77, v71
	v_cvt_f32_i32_e32 v166, v64
	v_cvt_f32_i32_e32 v167, v65
	v_cvt_f32_i32_e32 v82, v66
	v_cvt_f32_i32_e32 v83, v67
	v_cvt_f32_i32_e32 v70, v60
	v_cvt_f32_i32_e32 v71, v61
	v_cvt_f32_i32_e32 v74, v62
	v_cvt_f32_i32_e32 v75, v63
	v_cvt_f32_i32_e32 v68, v56
	v_cvt_f32_i32_e32 v69, v57
	v_cvt_f32_i32_e32 v72, v58
	v_cvt_f32_i32_e32 v73, v59
	v_cvt_f32_i32_e32 v62, v44
	v_cvt_f32_i32_e32 v63, v45
	v_cvt_f32_i32_e32 v66, v46
	v_cvt_f32_i32_e32 v67, v47
	v_cvt_f32_i32_e32 v60, v36
	v_cvt_f32_i32_e32 v61, v37
	v_cvt_f32_i32_e32 v64, v38
	v_cvt_f32_i32_e32 v65, v39
	v_cvt_f32_i32_e32 v56, v52
	v_cvt_f32_i32_e32 v57, v53
	v_cvt_f32_i32_e32 v58, v54
	v_cvt_f32_i32_e32 v59, v55
	v_cvt_f32_i32_e32 v52, v48
	v_cvt_f32_i32_e32 v53, v49
	v_cvt_f32_i32_e32 v54, v50
	v_cvt_f32_i32_e32 v55, v51
	v_cvt_f32_i32_e32 v46, v28
	v_cvt_f32_i32_e32 v47, v29
	v_cvt_f32_i32_e32 v50, v30
	v_cvt_f32_i32_e32 v51, v31
	v_cvt_f32_i32_e32 v44, v20
	v_cvt_f32_i32_e32 v45, v21
	v_cvt_f32_i32_e32 v48, v22
	v_cvt_f32_i32_e32 v49, v23
	v_cvt_f32_i32_e32 v38, v40
	v_cvt_f32_i32_e32 v39, v41
	v_cvt_f32_i32_e32 v42, v42
	v_cvt_f32_i32_e32 v43, v43
	v_cvt_f32_i32_e32 v36, v32
	v_cvt_f32_i32_e32 v37, v33
	v_cvt_f32_i32_e32 v40, v34
	v_cvt_f32_i32_e32 v41, v35
	v_cvt_f32_i32_e32 v30, v12
	v_cvt_f32_i32_e32 v31, v13
	v_cvt_f32_i32_e32 v34, v14
	v_cvt_f32_i32_e32 v35, v15
	v_cvt_f32_i32_e32 v28, v8
	v_cvt_f32_i32_e32 v29, v9
	v_cvt_f32_i32_e32 v32, v10
	v_cvt_f32_i32_e32 v33, v11
	v_cvt_f32_i32_e32 v22, v24
	v_cvt_f32_i32_e32 v23, v25
	v_cvt_f32_i32_e32 v26, v26
	v_cvt_f32_i32_e32 v27, v27
	v_cvt_f32_i32_e32 v20, v16
	v_cvt_f32_i32_e32 v21, v17
	v_cvt_f32_i32_e32 v24, v18
	v_cvt_f32_i32_e32 v25, v19
	v_cvt_f32_i32_e32 v14, v4
	v_cvt_f32_i32_e32 v15, v5
	v_cvt_f32_i32_e32 v18, v6
	v_cvt_f32_i32_e32 v19, v7
	v_cvt_f32_i32_e32 v12, v0
	v_cvt_f32_i32_e32 v13, v1
	v_cvt_f32_i32_e32 v16, v2
	v_cvt_f32_i32_e32 v17, v3
	s_and_b64 vcc, exec, s[20:21]
	s_cbranch_vccz .LBB0_1477
